# scan helper: gated-norm weights held in registers instead of 8 LDS reads per step; MLA row-max without canonicalising v_max; relaxed helper vmcnt
# speedup vs baseline: 1.0146x; 1.0034x over previous
.LBB0_861:
	s_waitcnt lgkmcnt(0)
	s_barrier
	s_waitcnt vmcnt(0)
	v_add_u32_e32 v3, 0x20600, v135
	ds_read_b128 v[48:51], v3
	ds_read_b128 v[36:39], v3 offset:16
	ds_read_b128 v[28:31], v3 offset:32
	ds_read_b128 v[16:19], v3 offset:48
	ds_read_b128 v[52:55], v3 offset:64
	ds_read_b128 v[40:43], v3 offset:80
	ds_read_b128 v[32:35], v3 offset:96
	ds_read_b128 v[24:27], v3 offset:112
	s_waitcnt lgkmcnt(6)
	v_and_b32_e32 v47, 0xffff0000, v36
	v_and_b32_e32 v46, 0xffff0000, v48
	v_lshlrev_b32_e32 v45, 16, v36
	v_lshlrev_b32_e32 v44, 16, v48
	v_pk_mul_f32 v[46:47], v[46:47], v[46:47]
	s_waitcnt lgkmcnt(4)
	v_and_b32_e32 v57, 0xffff0000, v16
	v_pk_fma_f32 v[44:45], v[44:45], v[44:45], v[46:47]
	v_lshlrev_b32_e32 v47, 16, v37
	v_lshlrev_b32_e32 v46, 16, v49
	v_pk_fma_f32 v[44:45], v[46:47], v[46:47], v[44:45]
	v_and_b32_e32 v47, 0xffff0000, v37
	v_and_b32_e32 v46, 0xffff0000, v49
	v_pk_fma_f32 v[44:45], v[46:47], v[46:47], v[44:45]
	v_lshlrev_b32_e32 v47, 16, v38
	v_lshlrev_b32_e32 v46, 16, v50
	v_pk_fma_f32 v[44:45], v[46:47], v[46:47], v[44:45]
	v_and_b32_e32 v47, 0xffff0000, v38
	v_and_b32_e32 v46, 0xffff0000, v50
	v_pk_fma_f32 v[44:45], v[46:47], v[46:47], v[44:45]
	v_lshlrev_b32_e32 v47, 16, v39
	v_lshlrev_b32_e32 v46, 16, v51
	v_pk_fma_f32 v[44:45], v[46:47], v[46:47], v[44:45]
	v_and_b32_e32 v47, 0xffff0000, v39
	v_and_b32_e32 v46, 0xffff0000, v51
	v_and_b32_e32 v56, 0xffff0000, v28
	v_pk_fma_f32 v[44:45], v[46:47], v[46:47], v[44:45]
	v_lshlrev_b32_e32 v47, 16, v16
	v_lshlrev_b32_e32 v46, 16, v28
	v_pk_mul_f32 v[56:57], v[56:57], v[56:57]
	s_waitcnt lgkmcnt(2)
	v_and_b32_e32 v59, 0xffff0000, v40
	v_pk_fma_f32 v[46:47], v[46:47], v[46:47], v[56:57]
	v_lshlrev_b32_e32 v57, 16, v17
	v_lshlrev_b32_e32 v56, 16, v29
	v_pk_fma_f32 v[46:47], v[56:57], v[56:57], v[46:47]
	v_and_b32_e32 v57, 0xffff0000, v17
	v_and_b32_e32 v56, 0xffff0000, v29
	v_pk_fma_f32 v[46:47], v[56:57], v[56:57], v[46:47]
	v_lshlrev_b32_e32 v57, 16, v18
	v_lshlrev_b32_e32 v56, 16, v30
	v_pk_fma_f32 v[46:47], v[56:57], v[56:57], v[46:47]
	v_and_b32_e32 v57, 0xffff0000, v18
	v_and_b32_e32 v56, 0xffff0000, v30
	v_pk_fma_f32 v[46:47], v[56:57], v[56:57], v[46:47]
	v_lshlrev_b32_e32 v57, 16, v19
	v_lshlrev_b32_e32 v56, 16, v31
	v_pk_fma_f32 v[46:47], v[56:57], v[56:57], v[46:47]
	v_and_b32_e32 v57, 0xffff0000, v19
	v_and_b32_e32 v56, 0xffff0000, v31
	v_and_b32_e32 v58, 0xffff0000, v52
	v_pk_fma_f32 v[46:47], v[56:57], v[56:57], v[46:47]
	v_lshlrev_b32_e32 v57, 16, v40
	v_lshlrev_b32_e32 v56, 16, v52
	v_pk_mul_f32 v[58:59], v[58:59], v[58:59]
	s_waitcnt lgkmcnt(0)
	v_and_b32_e32 v61, 0xffff0000, v24
	v_pk_fma_f32 v[56:57], v[56:57], v[56:57], v[58:59]
	v_lshlrev_b32_e32 v59, 16, v41
	v_lshlrev_b32_e32 v58, 16, v53
	v_pk_fma_f32 v[56:57], v[58:59], v[58:59], v[56:57]
	v_and_b32_e32 v59, 0xffff0000, v41
	v_and_b32_e32 v58, 0xffff0000, v53
	v_pk_fma_f32 v[56:57], v[58:59], v[58:59], v[56:57]
	v_lshlrev_b32_e32 v59, 16, v42
	v_lshlrev_b32_e32 v58, 16, v54
	v_pk_fma_f32 v[56:57], v[58:59], v[58:59], v[56:57]
	v_and_b32_e32 v59, 0xffff0000, v42
	v_and_b32_e32 v58, 0xffff0000, v54
	v_pk_fma_f32 v[56:57], v[58:59], v[58:59], v[56:57]
	v_lshlrev_b32_e32 v59, 16, v43
	v_lshlrev_b32_e32 v58, 16, v55
	v_pk_fma_f32 v[56:57], v[58:59], v[58:59], v[56:57]
	v_and_b32_e32 v59, 0xffff0000, v43
	v_and_b32_e32 v58, 0xffff0000, v55
	v_and_b32_e32 v60, 0xffff0000, v32
	v_pk_fma_f32 v[56:57], v[58:59], v[58:59], v[56:57]
	v_lshlrev_b32_e32 v59, 16, v24
	v_lshlrev_b32_e32 v58, 16, v32
	v_pk_mul_f32 v[60:61], v[60:61], v[60:61]
	v_add_f32_e32 v3, v44, v45
	v_pk_fma_f32 v[58:59], v[58:59], v[58:59], v[60:61]
	v_lshlrev_b32_e32 v61, 16, v25
	v_lshlrev_b32_e32 v60, 16, v33
	v_pk_fma_f32 v[58:59], v[60:61], v[60:61], v[58:59]
	v_and_b32_e32 v61, 0xffff0000, v25
	v_and_b32_e32 v60, 0xffff0000, v33
	v_pk_fma_f32 v[58:59], v[60:61], v[60:61], v[58:59]
	v_lshlrev_b32_e32 v61, 16, v26
	v_lshlrev_b32_e32 v60, 16, v34
	v_pk_fma_f32 v[58:59], v[60:61], v[60:61], v[58:59]
	v_and_b32_e32 v61, 0xffff0000, v26
	v_and_b32_e32 v60, 0xffff0000, v34
	v_add_f32_e32 v3, v3, v46
	v_pk_fma_f32 v[58:59], v[60:61], v[60:61], v[58:59]
	v_lshlrev_b32_e32 v61, 16, v27
	v_lshlrev_b32_e32 v60, 16, v35
	v_add_f32_e32 v3, v3, v47
	v_pk_fma_f32 v[58:59], v[60:61], v[60:61], v[58:59]
	v_and_b32_e32 v61, 0xffff0000, v27
	v_and_b32_e32 v60, 0xffff0000, v35
	v_add_f32_e32 v3, v3, v56
	v_pk_fma_f32 v[58:59], v[60:61], v[60:61], v[58:59]
	v_add_f32_e32 v3, v3, v57
	v_add_f32_e32 v3, v3, v58
	v_add_f32_e32 v3, v3, v59
	v_fmamk_f32 v3, v3, 0x3c800000, v134
	v_rsq_f32_e32 v46, v3
	v_or_b32_e32 v3, s12, v132
	v_mov_b64_e32 v[44:45], s[2:3]
	v_mad_i64_i32 v[44:45], s[8:9], v3, s73, v[44:45]
	v_mov_b32_e32 v3, s68
	v_cndmask_b32_e64 v54, v54, v50, s[6:7]
	v_lshlrev_b32_e32 v50, 16, v20
	s_waitcnt lgkmcnt(0)
	v_pk_mul_f32 v[62:63], v[214:215], v[46:47] op_sel_hi:[1,0]
	v_pk_mul_f32 v[58:59], v[210:211], v[46:47] op_sel_hi:[1,0]
	v_pk_mul_f32 v[56:57], v[208:209], v[46:47] op_sel_hi:[1,0]
	v_pk_mul_f32 v[60:61], v[212:213], v[46:47] op_sel_hi:[1,0]
	v_cndmask_b32_e64 v47, v55, v51, s[6:7]
	v_and_b32_e32 v51, 0xffff0000, v20
	v_mul_f32_e32 v20, 0xbfb8aa3b, v50
	v_cndmask_b32_e64 v55, v53, v49, s[6:7]
	v_exp_f32_e32 v20, v20
	v_mul_f32_e32 v49, 0xbfb8aa3b, v51
	v_exp_f32_e32 v49, v49
	v_cndmask_b32_e64 v53, v52, v48, s[6:7]
	v_add_f32_e32 v20, 1.0, v20
	v_rcp_f32_e32 v48, v20
	v_add_f32_e32 v20, 1.0, v49
	v_rcp_f32_e32 v49, v20
	v_lshlrev_b32_e32 v52, 16, v53
	v_and_b32_e32 v53, 0xffff0000, v53
	v_pk_mul_f32 v[52:53], v[56:57], v[52:53]
	v_pk_mul_f32 v[48:49], v[48:49], v[50:51]
	v_lshlrev_b32_e32 v50, 16, v21
	v_and_b32_e32 v51, 0xffff0000, v21
	v_mul_f32_e32 v20, 0xbfb8aa3b, v50
	v_exp_f32_e32 v21, v20
	v_mul_f32_e32 v20, 0xbfb8aa3b, v51
	v_pk_mul_f32 v[48:49], v[48:49], v[52:53]
	v_exp_f32_e32 v52, v20
	v_add_f32_e32 v21, 1.0, v21
	v_cvt_pk_bf16_f32 v20, v48, v49
	v_rcp_f32_e32 v48, v21
	v_add_f32_e32 v21, 1.0, v52
	v_rcp_f32_e32 v49, v21
	v_lshlrev_b32_e32 v52, 16, v55
	v_and_b32_e32 v53, 0xffff0000, v55
	v_pk_mul_f32 v[52:53], v[58:59], v[52:53]
	v_pk_mul_f32 v[48:49], v[48:49], v[50:51]
	v_lshlrev_b32_e32 v50, 16, v22
	v_and_b32_e32 v51, 0xffff0000, v22
	v_mul_f32_e32 v21, 0xbfb8aa3b, v50
	v_exp_f32_e32 v22, v21
	v_mul_f32_e32 v21, 0xbfb8aa3b, v51
	v_pk_mul_f32 v[48:49], v[48:49], v[52:53]
	v_exp_f32_e32 v52, v21
	v_add_f32_e32 v22, 1.0, v22
	v_cvt_pk_bf16_f32 v21, v48, v49
	v_rcp_f32_e32 v48, v22
	v_add_f32_e32 v22, 1.0, v52
	v_rcp_f32_e32 v49, v22
	v_lshlrev_b32_e32 v52, 16, v54
	v_and_b32_e32 v53, 0xffff0000, v54
	v_pk_mul_f32 v[52:53], v[60:61], v[52:53]
	v_pk_mul_f32 v[48:49], v[48:49], v[50:51]
	v_lshlrev_b32_e32 v50, 16, v23
	v_and_b32_e32 v51, 0xffff0000, v23
	v_mul_f32_e32 v22, 0xbfb8aa3b, v50
	v_exp_f32_e32 v23, v22
	v_mul_f32_e32 v22, 0xbfb8aa3b, v51
	v_pk_mul_f32 v[48:49], v[48:49], v[52:53]
	v_exp_f32_e32 v52, v22
	v_add_f32_e32 v23, 1.0, v23
	v_cvt_pk_bf16_f32 v22, v48, v49
	v_rcp_f32_e32 v48, v23
	v_add_f32_e32 v23, 1.0, v52
	v_rcp_f32_e32 v49, v23
	v_lshlrev_b32_e32 v52, 16, v47
	v_and_b32_e32 v53, 0xffff0000, v47
	s_lshl_b32 s12, s28, 1
	v_pk_mul_f32 v[52:53], v[62:63], v[52:53]
	v_pk_mul_f32 v[48:49], v[48:49], v[50:51]
	v_lshl_add_u64 v[44:45], v[44:45], 0, s[12:13]
	v_pk_mul_f32 v[48:49], v[48:49], v[52:53]
	v_cndmask_b32_e64 v42, v42, v38, s[6:7]
	v_lshlrev_b32_e32 v38, 16, v12
	v_lshl_add_u64 v[44:45], s[20:21], 1, v[44:45]
	v_cvt_pk_bf16_f32 v23, v48, v49
	v_cndmask_b32_e64 v43, v43, v39, s[6:7]
	v_and_b32_e32 v39, 0xffff0000, v12
	v_mul_f32_e32 v12, 0xbfb8aa3b, v38
	global_store_dwordx4 v[44:45], v[20:23], off
	s_waitcnt lgkmcnt(0)
	v_pk_mul_f32 v[48:49], v[222:223], v[46:47] op_sel_hi:[1,0]
	v_pk_mul_f32 v[50:51], v[220:221], v[46:47] op_sel_hi:[1,0]
	v_pk_mul_f32 v[20:21], v[218:219], v[46:47] op_sel_hi:[1,0]
	v_pk_mul_f32 v[22:23], v[216:217], v[46:47] op_sel_hi:[1,0]
	v_cndmask_b32_e64 v47, v41, v37, s[6:7]
	v_exp_f32_e32 v12, v12
	v_mul_f32_e32 v37, 0xbfb8aa3b, v39
	v_exp_f32_e32 v37, v37
	v_cndmask_b32_e64 v41, v40, v36, s[6:7]
	v_add_f32_e32 v12, 1.0, v12
	v_rcp_f32_e32 v36, v12
	v_add_f32_e32 v12, 1.0, v37
	v_rcp_f32_e32 v37, v12
	v_lshlrev_b32_e32 v40, 16, v41
	v_and_b32_e32 v41, 0xffff0000, v41
	v_pk_mul_f32 v[22:23], v[22:23], v[40:41]
	v_pk_mul_f32 v[36:37], v[36:37], v[38:39]
	v_and_b32_e32 v39, 0xffff0000, v47
	v_pk_mul_f32 v[22:23], v[36:37], v[22:23]
	v_lshlrev_b32_e32 v36, 16, v13
	v_and_b32_e32 v37, 0xffff0000, v13
	v_mul_f32_e32 v12, 0xbfb8aa3b, v36
	v_exp_f32_e32 v13, v12
	v_mul_f32_e32 v12, 0xbfb8aa3b, v37
	v_exp_f32_e32 v38, v12
	v_cvt_pk_bf16_f32 v12, v22, v23
	v_add_f32_e32 v13, 1.0, v13
	v_rcp_f32_e32 v22, v13
	v_add_f32_e32 v13, 1.0, v38
	v_rcp_f32_e32 v23, v13
	v_lshlrev_b32_e32 v38, 16, v47
	v_pk_mul_f32 v[20:21], v[20:21], v[38:39]
	v_cndmask_b32_e64 v34, v34, v30, s[6:7]
	v_pk_mul_f32 v[22:23], v[22:23], v[36:37]
	v_and_b32_e32 v37, 0xffff0000, v42
	v_pk_mul_f32 v[20:21], v[22:23], v[20:21]
	v_lshlrev_b32_e32 v22, 16, v14
	v_and_b32_e32 v23, 0xffff0000, v14
	v_mul_f32_e32 v13, 0xbfb8aa3b, v22
	v_exp_f32_e32 v14, v13
	v_mul_f32_e32 v13, 0xbfb8aa3b, v23
	v_exp_f32_e32 v36, v13
	v_cvt_pk_bf16_f32 v13, v20, v21
	v_add_f32_e32 v14, 1.0, v14
	v_rcp_f32_e32 v20, v14
	v_add_f32_e32 v14, 1.0, v36
	v_rcp_f32_e32 v21, v14
	v_lshlrev_b32_e32 v36, 16, v42
	v_pk_mul_f32 v[36:37], v[50:51], v[36:37]
	v_lshlrev_b32_e32 v30, 16, v8
	v_pk_mul_f32 v[20:21], v[20:21], v[22:23]
	v_lshlrev_b32_e32 v22, 16, v15
	v_and_b32_e32 v23, 0xffff0000, v15
	v_mul_f32_e32 v14, 0xbfb8aa3b, v22
	v_exp_f32_e32 v15, v14
	v_mul_f32_e32 v14, 0xbfb8aa3b, v23
	v_pk_mul_f32 v[20:21], v[20:21], v[36:37]
	v_exp_f32_e32 v36, v14
	v_add_f32_e32 v15, 1.0, v15
	v_cvt_pk_bf16_f32 v14, v20, v21
	v_rcp_f32_e32 v20, v15
	v_add_f32_e32 v15, 1.0, v36
	v_rcp_f32_e32 v21, v15
	v_lshlrev_b32_e32 v36, 16, v43
	v_and_b32_e32 v37, 0xffff0000, v43
	v_pk_mul_f32 v[36:37], v[48:49], v[36:37]
	v_pk_mul_f32 v[38:39], v[20:21], v[22:23]
	v_pk_mul_f32 v[40:41], v[38:39], v[36:37]
	v_cvt_pk_bf16_f32 v15, v40, v41
	v_cndmask_b32_e64 v35, v35, v31, s[6:7]
	v_and_b32_e32 v31, 0xffff0000, v8
	v_mul_f32_e32 v8, 0xbfb8aa3b, v30
	global_store_dwordx4 v[44:45], v[12:15], off offset:16
	v_exp_f32_e32 v8, v8
	s_waitcnt lgkmcnt(0)
	v_pk_mul_f32 v[12:13], v[226:227], v[46:47] op_sel_hi:[1,0]
	s_waitcnt lgkmcnt(0)
	v_pk_mul_f32 v[22:23], v[228:229], v[46:47] op_sel_hi:[1,0]
	v_cndmask_b32_e64 v36, v33, v29, s[6:7]
	v_mul_f32_e32 v29, 0xbfb8aa3b, v31
	v_exp_f32_e32 v29, v29
	v_add_f32_e32 v8, 1.0, v8
	v_cndmask_b32_e64 v33, v32, v28, s[6:7]
	v_rcp_f32_e32 v28, v8
	v_add_f32_e32 v8, 1.0, v29
	v_rcp_f32_e32 v29, v8
	v_pk_mul_f32 v[14:15], v[224:225], v[46:47] op_sel_hi:[1,0]
	v_lshlrev_b32_e32 v32, 16, v33
	v_and_b32_e32 v33, 0xffff0000, v33
	v_pk_mul_f32 v[14:15], v[14:15], v[32:33]
	v_pk_mul_f32 v[28:29], v[28:29], v[30:31]
	v_and_b32_e32 v31, 0xffff0000, v36
	v_pk_mul_f32 v[14:15], v[28:29], v[14:15]
	v_lshlrev_b32_e32 v28, 16, v9
	v_and_b32_e32 v29, 0xffff0000, v9
	v_mul_f32_e32 v8, 0xbfb8aa3b, v28
	v_exp_f32_e32 v9, v8
	v_mul_f32_e32 v8, 0xbfb8aa3b, v29
	v_exp_f32_e32 v30, v8
	v_cvt_pk_bf16_f32 v8, v14, v15
	v_add_f32_e32 v9, 1.0, v9
	v_rcp_f32_e32 v14, v9
	v_add_f32_e32 v9, 1.0, v30
	v_rcp_f32_e32 v15, v9
	v_lshlrev_b32_e32 v30, 16, v36
	v_pk_mul_f32 v[12:13], v[12:13], v[30:31]
	v_pk_mul_f32 v[20:21], v[230:231], v[46:47] op_sel_hi:[1,0]
	v_pk_mul_f32 v[14:15], v[14:15], v[28:29]
	v_and_b32_e32 v29, 0xffff0000, v34
	v_pk_mul_f32 v[12:13], v[14:15], v[12:13]
	v_lshlrev_b32_e32 v14, 16, v10
	v_and_b32_e32 v15, 0xffff0000, v10
	v_mul_f32_e32 v9, 0xbfb8aa3b, v14
	v_exp_f32_e32 v10, v9
	v_mul_f32_e32 v9, 0xbfb8aa3b, v15
	v_exp_f32_e32 v28, v9
	v_cvt_pk_bf16_f32 v9, v12, v13
	v_add_f32_e32 v10, 1.0, v10
	v_rcp_f32_e32 v12, v10
	v_add_f32_e32 v10, 1.0, v28
	v_rcp_f32_e32 v13, v10
	v_lshlrev_b32_e32 v28, 16, v34
	v_pk_mul_f32 v[22:23], v[22:23], v[28:29]
	v_pk_mul_f32 v[12:13], v[12:13], v[14:15]
	v_lshlrev_b32_e32 v14, 16, v11
	v_and_b32_e32 v15, 0xffff0000, v11
	v_mul_f32_e32 v10, 0xbfb8aa3b, v14
	v_exp_f32_e32 v11, v10
	v_mul_f32_e32 v10, 0xbfb8aa3b, v15
	v_pk_mul_f32 v[12:13], v[12:13], v[22:23]
	v_exp_f32_e32 v22, v10
	v_add_f32_e32 v11, 1.0, v11
	v_cvt_pk_bf16_f32 v10, v12, v13
	v_rcp_f32_e32 v12, v11
	v_add_f32_e32 v11, 1.0, v22
	v_rcp_f32_e32 v13, v11
	v_lshlrev_b32_e32 v22, 16, v35
	v_and_b32_e32 v23, 0xffff0000, v35
	v_pk_mul_f32 v[20:21], v[20:21], v[22:23]
	v_pk_mul_f32 v[22:23], v[12:13], v[14:15]
	v_pk_mul_f32 v[28:29], v[22:23], v[20:21]
	v_cvt_pk_bf16_f32 v11, v28, v29
	global_store_dwordx4 v[44:45], v[8:11], off offset:32
	v_cndmask_b32_e64 v3, v27, v19, s[6:7]
	v_and_b32_e32 v19, 0xffff0000, v4
	s_waitcnt lgkmcnt(0)
	v_pk_mul_f32 v[10:11], v[232:233], v[46:47] op_sel_hi:[1,0]
	s_waitcnt lgkmcnt(0)
	v_pk_mul_f32 v[12:13], v[238:239], v[46:47] op_sel_hi:[1,0]
	v_cndmask_b32_e64 v22, v26, v18, s[6:7]
	v_lshlrev_b32_e32 v18, 16, v4
	v_mul_f32_e32 v4, 0xbfb8aa3b, v18
	v_cndmask_b32_e64 v23, v25, v17, s[6:7]
	v_exp_f32_e32 v4, v4
	v_mul_f32_e32 v17, 0xbfb8aa3b, v19
	v_exp_f32_e32 v17, v17
	v_pk_mul_f32 v[8:9], v[234:235], v[46:47] op_sel_hi:[1,0]
	v_add_f32_e32 v4, 1.0, v4
	v_pk_mul_f32 v[14:15], v[236:237], v[46:47] op_sel_hi:[1,0]
	v_cndmask_b32_e64 v21, v24, v16, s[6:7]
	v_rcp_f32_e32 v16, v4
	v_add_f32_e32 v4, 1.0, v17
	v_rcp_f32_e32 v17, v4
	v_lshlrev_b32_e32 v20, 16, v21
	v_and_b32_e32 v21, 0xffff0000, v21
	v_pk_mul_f32 v[10:11], v[10:11], v[20:21]
	v_pk_mul_f32 v[16:17], v[16:17], v[18:19]
	v_and_b32_e32 v19, 0xffff0000, v23
	v_pk_mul_f32 v[10:11], v[16:17], v[10:11]
	v_lshlrev_b32_e32 v16, 16, v5
	v_and_b32_e32 v17, 0xffff0000, v5
	v_mul_f32_e32 v4, 0xbfb8aa3b, v16
	v_exp_f32_e32 v5, v4
	v_mul_f32_e32 v4, 0xbfb8aa3b, v17
	v_exp_f32_e32 v18, v4
	v_cvt_pk_bf16_f32 v4, v10, v11
	v_add_f32_e32 v5, 1.0, v5
	v_rcp_f32_e32 v10, v5
	v_add_f32_e32 v5, 1.0, v18
	v_rcp_f32_e32 v11, v5
	v_lshlrev_b32_e32 v18, 16, v23
	v_pk_mul_f32 v[8:9], v[8:9], v[18:19]
	v_pk_mul_f32 v[10:11], v[10:11], v[16:17]
	s_nop 0
	v_pk_mul_f32 v[8:9], v[10:11], v[8:9]
	v_lshlrev_b32_e32 v10, 16, v6
	v_and_b32_e32 v11, 0xffff0000, v6
	v_mul_f32_e32 v5, 0xbfb8aa3b, v10
	v_exp_f32_e32 v6, v5
	v_mul_f32_e32 v5, 0xbfb8aa3b, v11
	v_exp_f32_e32 v16, v5
	v_cvt_pk_bf16_f32 v5, v8, v9
	v_add_f32_e32 v6, 1.0, v6
	v_rcp_f32_e32 v8, v6
	v_add_f32_e32 v6, 1.0, v16
	v_rcp_f32_e32 v9, v6
	v_lshlrev_b32_e32 v16, 16, v22
	v_and_b32_e32 v17, 0xffff0000, v22
	v_pk_mul_f32 v[14:15], v[14:15], v[16:17]
	v_pk_mul_f32 v[8:9], v[8:9], v[10:11]
	v_lshlrev_b32_e32 v10, 16, v7
	v_and_b32_e32 v11, 0xffff0000, v7
	v_mul_f32_e32 v6, 0xbfb8aa3b, v10
	v_exp_f32_e32 v7, v6
	v_mul_f32_e32 v6, 0xbfb8aa3b, v11
	v_pk_mul_f32 v[8:9], v[8:9], v[14:15]
	v_exp_f32_e32 v14, v6
	v_add_f32_e32 v7, 1.0, v7
	v_cvt_pk_bf16_f32 v6, v8, v9
	v_rcp_f32_e32 v8, v7
	v_add_f32_e32 v7, 1.0, v14
	v_rcp_f32_e32 v9, v7
	v_lshlrev_b32_e32 v14, 16, v3
	v_and_b32_e32 v15, 0xffff0000, v3
	v_pk_mul_f32 v[12:13], v[12:13], v[14:15]
	v_pk_mul_f32 v[8:9], v[8:9], v[10:11]
	s_nop 0
	v_pk_mul_f32 v[8:9], v[8:9], v[12:13]
	s_nop 0
	v_cvt_pk_bf16_f32 v7, v8, v9
	global_store_dwordx4 v[44:45], v[4:7], off offset:48

; #define LBAR() do { asm volatile("s_waitcnt lgkmcnt(0)" ::: "memory"); __builtin_amdgcn_s_barrier(); asm volatile("" ::: "memory"); } while (0)
; #define GZLOAD(ZR, chunk) do { const bf16_t* zp_ = proj + (size_t)(b * SEQ + (chunk) * 64 + lane) * NINP + C_GZ + h * 64 + 32 * hc; \
;         _Pragma("unroll") for (int k = 0; k < 4; ++k) ZR[k] = *(const u32x4*)(zp_ + 8 * k); } while (0)
; DI void gdn_scan(const Ctx& c, int bh, const unsigned char* gbase, const float* GL, bf16_t* proj, const float* normw) {
;     ...
;     if (wid >= 6) {
;         const int hc = wid - 6;
;         u32x4 zA[4], zB[4];
;         GZLOAD(zA, 0);
;         for (int n = 0; n < 64; n += 2) {
;             LBAR(); if (n > 0) GHELP(n - 1, zB); GZLOAD(zB, n + 1);
;             LBAR(); GHELP(n, zA); { const int nx = n + 2 < 64 ? n + 2 : 63; GZLOAD(zA, nx); }
.LBB0_884:
	s_nop 0
	v_add_u32_e32 v4, s33, v64
	v_mov_b64_e32 v[60:61], s[8:9]
	v_mad_i64_i32 v[20:21], s[52:53], v4, s73, v[60:61]
	global_load_dwordx4 v[4:7], v[20:21], off offset:3120
	global_load_dwordx4 v[8:11], v[20:21], off offset:3104
	global_load_dwordx4 v[12:15], v[20:21], off offset:3088
	s_nop 0
	global_load_dwordx4 v[20:23], v[20:21], off offset:3072
	s_waitcnt lgkmcnt(0)
	s_barrier
	v_add_u32_e32 v40, 0x1e200, v135
	ds_read_b128 v[66:69], v40
	ds_read_b128 v[52:55], v40 offset:16
	ds_read_b128 v[44:47], v40 offset:32
	ds_read_b128 v[36:39], v40 offset:48
	ds_read_b128 v[70:73], v40 offset:64
	ds_read_b128 v[56:59], v40 offset:80
	ds_read_b128 v[48:51], v40 offset:96
	ds_read_b128 v[40:43], v40 offset:112
	s_waitcnt lgkmcnt(0)
	v_and_b32_e32 v77, 0xffff0000, v52
	v_and_b32_e32 v76, 0xffff0000, v66
	v_lshlrev_b32_e32 v75, 16, v52
	v_lshlrev_b32_e32 v74, 16, v66
	v_pk_mul_f32 v[76:77], v[76:77], v[76:77]
	v_and_b32_e32 v79, 0xffff0000, v36
	v_pk_fma_f32 v[74:75], v[74:75], v[74:75], v[76:77]
	v_lshlrev_b32_e32 v77, 16, v53
	v_lshlrev_b32_e32 v76, 16, v67
	v_pk_fma_f32 v[74:75], v[76:77], v[76:77], v[74:75]
	v_and_b32_e32 v77, 0xffff0000, v53
	v_and_b32_e32 v76, 0xffff0000, v67
	v_pk_fma_f32 v[74:75], v[76:77], v[76:77], v[74:75]
	v_lshlrev_b32_e32 v77, 16, v54
	v_lshlrev_b32_e32 v76, 16, v68
	v_pk_fma_f32 v[74:75], v[76:77], v[76:77], v[74:75]
	v_and_b32_e32 v77, 0xffff0000, v54
	v_and_b32_e32 v76, 0xffff0000, v68
	v_pk_fma_f32 v[74:75], v[76:77], v[76:77], v[74:75]
	v_lshlrev_b32_e32 v77, 16, v55
	v_lshlrev_b32_e32 v76, 16, v69
	v_pk_fma_f32 v[74:75], v[76:77], v[76:77], v[74:75]
	v_and_b32_e32 v77, 0xffff0000, v55
	v_and_b32_e32 v76, 0xffff0000, v69
	v_and_b32_e32 v78, 0xffff0000, v44
	v_pk_fma_f32 v[74:75], v[76:77], v[76:77], v[74:75]
	v_lshlrev_b32_e32 v77, 16, v36
	v_lshlrev_b32_e32 v76, 16, v44
	v_pk_mul_f32 v[78:79], v[78:79], v[78:79]
	v_and_b32_e32 v81, 0xffff0000, v56
	v_pk_fma_f32 v[76:77], v[76:77], v[76:77], v[78:79]
	v_lshlrev_b32_e32 v79, 16, v37
	v_lshlrev_b32_e32 v78, 16, v45
	v_pk_fma_f32 v[76:77], v[78:79], v[78:79], v[76:77]
	v_and_b32_e32 v79, 0xffff0000, v37
	v_and_b32_e32 v78, 0xffff0000, v45
	v_pk_fma_f32 v[76:77], v[78:79], v[78:79], v[76:77]
	v_lshlrev_b32_e32 v79, 16, v38
	v_lshlrev_b32_e32 v78, 16, v46
	v_pk_fma_f32 v[76:77], v[78:79], v[78:79], v[76:77]
	v_and_b32_e32 v79, 0xffff0000, v38
	v_and_b32_e32 v78, 0xffff0000, v46
	v_pk_fma_f32 v[76:77], v[78:79], v[78:79], v[76:77]
	v_lshlrev_b32_e32 v79, 16, v39
	v_lshlrev_b32_e32 v78, 16, v47
	v_pk_fma_f32 v[76:77], v[78:79], v[78:79], v[76:77]
	v_and_b32_e32 v79, 0xffff0000, v39
	v_and_b32_e32 v78, 0xffff0000, v47
	v_and_b32_e32 v80, 0xffff0000, v70
	v_pk_fma_f32 v[76:77], v[78:79], v[78:79], v[76:77]
	v_lshlrev_b32_e32 v79, 16, v56
	v_lshlrev_b32_e32 v78, 16, v70
	v_pk_mul_f32 v[80:81], v[80:81], v[80:81]
	v_and_b32_e32 v83, 0xffff0000, v40
	v_pk_fma_f32 v[78:79], v[78:79], v[78:79], v[80:81]
	v_lshlrev_b32_e32 v81, 16, v57
	v_lshlrev_b32_e32 v80, 16, v71
	v_pk_fma_f32 v[78:79], v[80:81], v[80:81], v[78:79]
	v_and_b32_e32 v81, 0xffff0000, v57
	v_and_b32_e32 v80, 0xffff0000, v71
	v_pk_fma_f32 v[78:79], v[80:81], v[80:81], v[78:79]
	v_lshlrev_b32_e32 v81, 16, v58
	v_lshlrev_b32_e32 v80, 16, v72
	v_pk_fma_f32 v[78:79], v[80:81], v[80:81], v[78:79]
	v_and_b32_e32 v81, 0xffff0000, v58
	v_and_b32_e32 v80, 0xffff0000, v72
	v_pk_fma_f32 v[78:79], v[80:81], v[80:81], v[78:79]
	v_lshlrev_b32_e32 v81, 16, v59
	v_lshlrev_b32_e32 v80, 16, v73
	v_pk_fma_f32 v[78:79], v[80:81], v[80:81], v[78:79]
	v_and_b32_e32 v81, 0xffff0000, v59
	v_and_b32_e32 v80, 0xffff0000, v73
	v_and_b32_e32 v82, 0xffff0000, v48
	v_pk_fma_f32 v[78:79], v[80:81], v[80:81], v[78:79]
	v_lshlrev_b32_e32 v81, 16, v40
	v_lshlrev_b32_e32 v80, 16, v48
	v_pk_mul_f32 v[82:83], v[82:83], v[82:83]
	v_add_u32_e32 v65, s33, v63
	v_pk_fma_f32 v[80:81], v[80:81], v[80:81], v[82:83]
	v_lshlrev_b32_e32 v83, 16, v41
	v_lshlrev_b32_e32 v82, 16, v49
	v_pk_fma_f32 v[80:81], v[82:83], v[82:83], v[80:81]
	v_and_b32_e32 v83, 0xffff0000, v41
	v_and_b32_e32 v82, 0xffff0000, v49
	v_cndmask_b32_e64 v72, v72, v68, s[6:7]
	s_waitcnt vmcnt(4)
	v_lshlrev_b32_e32 v68, 16, v32
	v_pk_fma_f32 v[80:81], v[82:83], v[82:83], v[80:81]
	v_lshlrev_b32_e32 v83, 16, v42
	v_lshlrev_b32_e32 v82, 16, v50
	v_add_f32_e32 v62, v74, v75
	v_mad_i64_i32 v[60:61], s[52:53], v65, s73, v[60:61]
	v_cndmask_b32_e64 v65, v73, v69, s[6:7]
	v_and_b32_e32 v69, 0xffff0000, v32
	v_mul_f32_e32 v32, 0xbfb8aa3b, v68
	v_pk_fma_f32 v[80:81], v[82:83], v[82:83], v[80:81]
	v_and_b32_e32 v83, 0xffff0000, v42
	v_and_b32_e32 v82, 0xffff0000, v50
	v_add_f32_e32 v62, v62, v76
	v_cndmask_b32_e64 v73, v71, v67, s[6:7]
	v_exp_f32_e32 v32, v32
	v_mul_f32_e32 v67, 0xbfb8aa3b, v69
	v_pk_fma_f32 v[80:81], v[82:83], v[82:83], v[80:81]
	v_lshlrev_b32_e32 v83, 16, v43
	v_lshlrev_b32_e32 v82, 16, v51
	v_add_f32_e32 v62, v62, v77
	v_exp_f32_e32 v67, v67
	v_pk_fma_f32 v[80:81], v[82:83], v[82:83], v[80:81]
	v_and_b32_e32 v83, 0xffff0000, v43
	v_and_b32_e32 v82, 0xffff0000, v51
	v_add_f32_e32 v62, v62, v78
	v_pk_fma_f32 v[80:81], v[82:83], v[82:83], v[80:81]
	v_add_f32_e32 v62, v62, v79
	v_add_f32_e32 v62, v62, v80
	v_add_f32_e32 v32, 1.0, v32
	v_add_f32_e32 v62, v62, v81
	v_mov_b32_e32 v90, s68
	v_cndmask_b32_e64 v71, v70, v66, s[6:7]
	v_rcp_f32_e32 v66, v32
	v_add_f32_e32 v32, 1.0, v67
	v_fmamk_f32 v62, v62, 0x3c800000, v134
	v_rcp_f32_e32 v67, v32
	v_rsq_f32_e32 v62, v62
	v_lshlrev_b32_e32 v70, 16, v71
	v_and_b32_e32 v71, 0xffff0000, v71
	v_pk_mul_f32 v[66:67], v[66:67], v[68:69]
	v_lshlrev_b32_e32 v68, 16, v33
	s_waitcnt lgkmcnt(0)
	v_pk_mul_f32 v[74:75], v[208:209], v[62:63] op_sel_hi:[1,0]
	v_and_b32_e32 v69, 0xffff0000, v33
	v_mul_f32_e32 v32, 0xbfb8aa3b, v68
	v_pk_mul_f32 v[70:71], v[74:75], v[70:71]
	v_exp_f32_e32 v33, v32
	v_mul_f32_e32 v32, 0xbfb8aa3b, v69
	v_pk_mul_f32 v[66:67], v[66:67], v[70:71]
	v_exp_f32_e32 v70, v32
	v_add_f32_e32 v33, 1.0, v33
	v_cvt_pk_bf16_f32 v32, v66, v67
	v_rcp_f32_e32 v66, v33
	v_add_f32_e32 v33, 1.0, v70
	v_rcp_f32_e32 v67, v33
	v_pk_mul_f32 v[76:77], v[210:211], v[62:63] op_sel_hi:[1,0]
	v_lshlrev_b32_e32 v70, 16, v73
	v_and_b32_e32 v71, 0xffff0000, v73
	v_pk_mul_f32 v[66:67], v[66:67], v[68:69]
	v_lshlrev_b32_e32 v68, 16, v34
	v_and_b32_e32 v69, 0xffff0000, v34
	v_mul_f32_e32 v33, 0xbfb8aa3b, v68
	v_pk_mul_f32 v[70:71], v[76:77], v[70:71]
	v_exp_f32_e32 v34, v33
	v_mul_f32_e32 v33, 0xbfb8aa3b, v69
	v_pk_mul_f32 v[66:67], v[66:67], v[70:71]
	v_exp_f32_e32 v70, v33
	v_add_f32_e32 v34, 1.0, v34
	v_cvt_pk_bf16_f32 v33, v66, v67
	v_rcp_f32_e32 v66, v34
	v_add_f32_e32 v34, 1.0, v70
	v_rcp_f32_e32 v67, v34
	v_lshlrev_b32_e32 v70, 16, v72
	v_and_b32_e32 v71, 0xffff0000, v72
	v_pk_mul_f32 v[66:67], v[66:67], v[68:69]
	v_lshlrev_b32_e32 v68, 16, v35
	s_waitcnt lgkmcnt(0)
	v_pk_mul_f32 v[78:79], v[212:213], v[62:63] op_sel_hi:[1,0]
	v_and_b32_e32 v69, 0xffff0000, v35
	v_mul_f32_e32 v34, 0xbfb8aa3b, v68
	v_pk_mul_f32 v[70:71], v[78:79], v[70:71]
	v_exp_f32_e32 v35, v34
	v_mul_f32_e32 v34, 0xbfb8aa3b, v69
	v_pk_mul_f32 v[66:67], v[66:67], v[70:71]
	v_exp_f32_e32 v70, v34
	v_cndmask_b32_e64 v58, v58, v54, s[6:7]
	v_lshlrev_b32_e32 v54, 16, v28
	v_add_f32_e32 v35, 1.0, v35
	v_cndmask_b32_e64 v59, v59, v55, s[6:7]
	v_and_b32_e32 v55, 0xffff0000, v28
	v_mul_f32_e32 v28, 0xbfb8aa3b, v54
	v_cvt_pk_bf16_f32 v34, v66, v67
	v_rcp_f32_e32 v66, v35
	v_add_f32_e32 v35, 1.0, v70
	v_lshlrev_b32_e32 v70, 16, v65
	v_and_b32_e32 v71, 0xffff0000, v65
	v_cndmask_b32_e64 v65, v57, v53, s[6:7]
	v_exp_f32_e32 v28, v28
	v_mul_f32_e32 v53, 0xbfb8aa3b, v55
	v_exp_f32_e32 v53, v53
	v_rcp_f32_e32 v67, v35
	v_add_f32_e32 v28, 1.0, v28
	v_pk_mul_f32 v[80:81], v[214:215], v[62:63] op_sel_hi:[1,0]
	v_cndmask_b32_e64 v57, v56, v52, s[6:7]
	v_rcp_f32_e32 v52, v28
	v_add_f32_e32 v28, 1.0, v53
	v_pk_mul_f32 v[70:71], v[80:81], v[70:71]
	v_pk_mul_f32 v[66:67], v[66:67], v[68:69]
	v_rcp_f32_e32 v53, v28
	v_pk_mul_f32 v[66:67], v[66:67], v[70:71]
	v_lshlrev_b32_e32 v56, 16, v57
	v_cvt_pk_bf16_f32 v35, v66, v67
	global_store_dwordx4 v[60:61], v[32:35], off
	v_and_b32_e32 v57, 0xffff0000, v57
	v_pk_mul_f32 v[52:53], v[52:53], v[54:55]
	s_waitcnt lgkmcnt(0)
	v_pk_mul_f32 v[34:35], v[216:217], v[62:63] op_sel_hi:[1,0]
	v_pk_mul_f32 v[32:33], v[218:219], v[62:63] op_sel_hi:[1,0]
	v_pk_mul_f32 v[34:35], v[34:35], v[56:57]
	v_and_b32_e32 v55, 0xffff0000, v65
	v_pk_mul_f32 v[34:35], v[52:53], v[34:35]
	v_lshlrev_b32_e32 v52, 16, v29
	v_and_b32_e32 v53, 0xffff0000, v29
	v_mul_f32_e32 v28, 0xbfb8aa3b, v52
	v_exp_f32_e32 v29, v28
	v_mul_f32_e32 v28, 0xbfb8aa3b, v53
	v_exp_f32_e32 v54, v28
	v_cvt_pk_bf16_f32 v28, v34, v35
	v_add_f32_e32 v29, 1.0, v29
	v_rcp_f32_e32 v34, v29
	v_add_f32_e32 v29, 1.0, v54
	v_rcp_f32_e32 v35, v29
	v_lshlrev_b32_e32 v54, 16, v65
	v_pk_mul_f32 v[32:33], v[32:33], v[54:55]
	s_waitcnt lgkmcnt(0)
	v_pk_mul_f32 v[68:69], v[220:221], v[62:63] op_sel_hi:[1,0]
	v_pk_mul_f32 v[34:35], v[34:35], v[52:53]
	v_and_b32_e32 v53, 0xffff0000, v58
	v_pk_mul_f32 v[32:33], v[34:35], v[32:33]
	v_lshlrev_b32_e32 v34, 16, v30
	v_and_b32_e32 v35, 0xffff0000, v30
	v_mul_f32_e32 v29, 0xbfb8aa3b, v34
	v_exp_f32_e32 v30, v29
	v_mul_f32_e32 v29, 0xbfb8aa3b, v35
	v_exp_f32_e32 v52, v29
	v_cvt_pk_bf16_f32 v29, v32, v33
	v_add_f32_e32 v30, 1.0, v30
	v_rcp_f32_e32 v32, v30
	v_add_f32_e32 v30, 1.0, v52
	v_rcp_f32_e32 v33, v30
	v_lshlrev_b32_e32 v52, 16, v58
	v_pk_mul_f32 v[52:53], v[68:69], v[52:53]
	v_pk_mul_f32 v[66:67], v[222:223], v[62:63] op_sel_hi:[1,0]
	v_pk_mul_f32 v[32:33], v[32:33], v[34:35]
	v_lshlrev_b32_e32 v34, 16, v31
	v_and_b32_e32 v35, 0xffff0000, v31
	v_mul_f32_e32 v30, 0xbfb8aa3b, v34
	v_exp_f32_e32 v31, v30
	v_mul_f32_e32 v30, 0xbfb8aa3b, v35
	v_pk_mul_f32 v[32:33], v[32:33], v[52:53]
	v_exp_f32_e32 v52, v30
	v_add_f32_e32 v31, 1.0, v31
	v_cvt_pk_bf16_f32 v30, v32, v33
	v_rcp_f32_e32 v32, v31
	v_add_f32_e32 v31, 1.0, v52
	v_rcp_f32_e32 v33, v31
	v_lshlrev_b32_e32 v52, 16, v59
	v_and_b32_e32 v53, 0xffff0000, v59
	v_pk_mul_f32 v[52:53], v[66:67], v[52:53]
	v_pk_mul_f32 v[54:55], v[32:33], v[34:35]
	v_pk_mul_f32 v[56:57], v[54:55], v[52:53]
	v_cndmask_b32_e64 v50, v50, v46, s[6:7]
	v_lshlrev_b32_e32 v46, 16, v24
	v_cvt_pk_bf16_f32 v31, v56, v57
	v_cndmask_b32_e64 v51, v51, v47, s[6:7]
	v_and_b32_e32 v47, 0xffff0000, v24
	v_mul_f32_e32 v24, 0xbfb8aa3b, v46
	global_store_dwordx4 v[60:61], v[28:31], off offset:16
	v_exp_f32_e32 v24, v24
	v_cndmask_b32_e64 v41, v41, v37, s[6:7]
	s_waitcnt lgkmcnt(0)
	v_pk_mul_f32 v[28:29], v[226:227], v[62:63] op_sel_hi:[1,0]
	s_waitcnt lgkmcnt(0)
; #define LBAR() do { asm volatile("s_waitcnt lgkmcnt(0)" ::: "memory"); __builtin_amdgcn_s_barrier(); asm volatile("" ::: "memory"); } while (0)
; #define GZLOAD(ZR, chunk) do { const bf16_t* zp_ = proj + (size_t)(b * SEQ + (chunk) * 64 + lane) * NINP + C_GZ + h * 64 + 32 * hc; \
;         _Pragma("unroll") for (int k = 0; k < 4; ++k) ZR[k] = *(const u32x4*)(zp_ + 8 * k); } while (0)
; DI void gdn_scan(const Ctx& c, int bh, const unsigned char* gbase, const float* GL, bf16_t* proj, const float* normw) {
;     ...
;         for (int n = 0; n < 64; n += 2) {
;             LBAR(); if (n > 0) GHELP(n - 1, zB); GZLOAD(zB, n + 1);
;             LBAR(); GHELP(n, zA); { const int nx = n + 2 < 64 ? n + 2 : 63; GZLOAD(zA, nx); }
	v_pk_mul_f32 v[34:35], v[228:229], v[62:63] op_sel_hi:[1,0]
	v_cndmask_b32_e64 v52, v49, v45, s[6:7]
	v_mul_f32_e32 v45, 0xbfb8aa3b, v47
	v_exp_f32_e32 v45, v45
	v_add_f32_e32 v24, 1.0, v24
	v_cndmask_b32_e64 v49, v48, v44, s[6:7]
	v_rcp_f32_e32 v44, v24
	v_add_f32_e32 v24, 1.0, v45
	v_rcp_f32_e32 v45, v24
	v_pk_mul_f32 v[30:31], v[224:225], v[62:63] op_sel_hi:[1,0]
	v_lshlrev_b32_e32 v48, 16, v49
	v_and_b32_e32 v49, 0xffff0000, v49
	v_pk_mul_f32 v[30:31], v[30:31], v[48:49]
	v_pk_mul_f32 v[44:45], v[44:45], v[46:47]
	v_and_b32_e32 v47, 0xffff0000, v52
	v_pk_mul_f32 v[30:31], v[44:45], v[30:31]
	v_lshlrev_b32_e32 v44, 16, v25
	v_and_b32_e32 v45, 0xffff0000, v25
	v_mul_f32_e32 v24, 0xbfb8aa3b, v44
	v_exp_f32_e32 v25, v24
	v_mul_f32_e32 v24, 0xbfb8aa3b, v45
	v_exp_f32_e32 v46, v24
	v_cvt_pk_bf16_f32 v24, v30, v31
	v_add_f32_e32 v25, 1.0, v25
	v_rcp_f32_e32 v30, v25
	v_add_f32_e32 v25, 1.0, v46
	v_rcp_f32_e32 v31, v25
	v_lshlrev_b32_e32 v46, 16, v52
	v_pk_mul_f32 v[28:29], v[28:29], v[46:47]
	v_pk_mul_f32 v[32:33], v[230:231], v[62:63] op_sel_hi:[1,0]
	v_pk_mul_f32 v[30:31], v[30:31], v[44:45]
	v_and_b32_e32 v45, 0xffff0000, v50
	v_pk_mul_f32 v[28:29], v[30:31], v[28:29]
	v_lshlrev_b32_e32 v30, 16, v26
	v_and_b32_e32 v31, 0xffff0000, v26
	v_mul_f32_e32 v25, 0xbfb8aa3b, v30
	v_exp_f32_e32 v26, v25
	v_mul_f32_e32 v25, 0xbfb8aa3b, v31
	v_exp_f32_e32 v44, v25
	v_cvt_pk_bf16_f32 v25, v28, v29
	v_add_f32_e32 v26, 1.0, v26
	v_rcp_f32_e32 v28, v26
	v_add_f32_e32 v26, 1.0, v44
	v_rcp_f32_e32 v29, v26
	v_lshlrev_b32_e32 v44, 16, v50
	v_pk_mul_f32 v[34:35], v[34:35], v[44:45]
	v_cndmask_b32_e64 v37, v40, v36, s[6:7]
	v_pk_mul_f32 v[28:29], v[28:29], v[30:31]
	v_lshlrev_b32_e32 v30, 16, v27
	v_and_b32_e32 v31, 0xffff0000, v27
	v_mul_f32_e32 v26, 0xbfb8aa3b, v30
	v_exp_f32_e32 v27, v26
	v_mul_f32_e32 v26, 0xbfb8aa3b, v31
	v_pk_mul_f32 v[28:29], v[28:29], v[34:35]
	v_exp_f32_e32 v34, v26
	v_add_f32_e32 v27, 1.0, v27
	v_cvt_pk_bf16_f32 v26, v28, v29
	v_rcp_f32_e32 v28, v27
	v_add_f32_e32 v27, 1.0, v34
	v_rcp_f32_e32 v29, v27
	v_lshlrev_b32_e32 v34, 16, v51
	v_and_b32_e32 v35, 0xffff0000, v51
	v_pk_mul_f32 v[32:33], v[32:33], v[34:35]
	v_pk_mul_f32 v[34:35], v[28:29], v[30:31]
	v_pk_mul_f32 v[44:45], v[34:35], v[32:33]
	v_cvt_pk_bf16_f32 v27, v44, v45
	global_store_dwordx4 v[60:61], v[24:27], off offset:32
	v_lshlrev_b32_e32 v36, 16, v37
	v_and_b32_e32 v37, 0xffff0000, v37
	s_waitcnt lgkmcnt(0)
	v_pk_mul_f32 v[24:25], v[234:235], v[62:63] op_sel_hi:[1,0]
	s_waitcnt lgkmcnt(0)
	v_pk_mul_f32 v[30:31], v[236:237], v[62:63] op_sel_hi:[1,0]
	v_lshlrev_b32_e32 v32, 16, v16
	v_and_b32_e32 v33, 0xffff0000, v16
	v_mul_f32_e32 v16, 0xbfb8aa3b, v32
	v_pk_mul_f32 v[26:27], v[232:233], v[62:63] op_sel_hi:[1,0]
	v_pk_mul_f32 v[28:29], v[238:239], v[62:63] op_sel_hi:[1,0]
	v_exp_f32_e32 v16, v16
	v_mul_f32_e32 v34, 0xbfb8aa3b, v33
	v_exp_f32_e32 v35, v34
	v_pk_mul_f32 v[26:27], v[26:27], v[36:37]
	v_add_f32_e32 v16, 1.0, v16
	v_rcp_f32_e32 v34, v16
	v_add_f32_e32 v16, 1.0, v35
	v_rcp_f32_e32 v35, v16
	v_cndmask_b32_e64 v38, v42, v38, s[6:7]
	v_cndmask_b32_e64 v39, v43, v39, s[6:7]
	s_add_i32 s33, s36, 2
	v_pk_mul_f32 v[32:33], v[34:35], v[32:33]
	v_and_b32_e32 v35, 0xffff0000, v41
	v_pk_mul_f32 v[26:27], v[32:33], v[26:27]
	v_lshlrev_b32_e32 v32, 16, v17
	v_and_b32_e32 v33, 0xffff0000, v17
	v_mul_f32_e32 v16, 0xbfb8aa3b, v32
	v_exp_f32_e32 v17, v16
	v_mul_f32_e32 v16, 0xbfb8aa3b, v33
	v_exp_f32_e32 v34, v16
	v_cvt_pk_bf16_f32 v16, v26, v27
	v_add_f32_e32 v17, 1.0, v17
	v_rcp_f32_e32 v26, v17
	v_add_f32_e32 v17, 1.0, v34
	v_rcp_f32_e32 v27, v17
	v_lshlrev_b32_e32 v34, 16, v41
	v_pk_mul_f32 v[24:25], v[24:25], v[34:35]
	s_addk_i32 s29, 0x80
	v_pk_mul_f32 v[26:27], v[26:27], v[32:33]
	v_and_b32_e32 v33, 0xffff0000, v38
	v_pk_mul_f32 v[24:25], v[26:27], v[24:25]
	v_lshlrev_b32_e32 v26, 16, v18
	v_and_b32_e32 v27, 0xffff0000, v18
	v_mul_f32_e32 v17, 0xbfb8aa3b, v26
	v_exp_f32_e32 v18, v17
	v_mul_f32_e32 v17, 0xbfb8aa3b, v27
	v_exp_f32_e32 v32, v17
	v_cvt_pk_bf16_f32 v17, v24, v25
	v_add_f32_e32 v18, 1.0, v18
	v_rcp_f32_e32 v24, v18
	v_add_f32_e32 v18, 1.0, v32
	v_rcp_f32_e32 v25, v18
	v_lshlrev_b32_e32 v32, 16, v38
	v_pk_mul_f32 v[30:31], v[30:31], v[32:33]
	s_cmp_lt_u32 s36, 62
	v_pk_mul_f32 v[24:25], v[24:25], v[26:27]
	v_lshlrev_b32_e32 v26, 16, v19
	v_and_b32_e32 v27, 0xffff0000, v19
	v_mul_f32_e32 v18, 0xbfb8aa3b, v26
	v_exp_f32_e32 v19, v18
	v_mul_f32_e32 v18, 0xbfb8aa3b, v27
	v_pk_mul_f32 v[24:25], v[24:25], v[30:31]
	v_exp_f32_e32 v30, v18
	v_add_f32_e32 v19, 1.0, v19
	v_cvt_pk_bf16_f32 v18, v24, v25
	v_rcp_f32_e32 v24, v19
	v_add_f32_e32 v19, 1.0, v30
	v_rcp_f32_e32 v25, v19
	v_lshlrev_b32_e32 v30, 16, v39
	v_and_b32_e32 v31, 0xffff0000, v39
	v_pk_mul_f32 v[28:29], v[28:29], v[30:31]
	v_pk_mul_f32 v[24:25], v[24:25], v[26:27]
	s_cselect_b32 s37, s29, 0xfc0
	v_pk_mul_f32 v[24:25], v[24:25], v[28:29]
	s_cmp_gt_u32 s36, 61
	v_cvt_pk_bf16_f32 v19, v24, v25
	global_store_dwordx4 v[60:61], v[16:19], off offset:48
	s_mov_b32 s36, s33
	s_nop 0
	v_add_u32_e32 v16, s37, v63
	s_cbranch_scc1 .LBB0_861
; #define LBAR() do { asm volatile("s_waitcnt lgkmcnt(0)" ::: "memory"); __builtin_amdgcn_s_barrier(); asm volatile("" ::: "memory"); } while (0)
; #define GZLOAD(ZR, chunk) do { const bf16_t* zp_ = proj + (size_t)(b * SEQ + (chunk) * 64 + lane) * NINP + C_GZ + h * 64 + 32 * hc; \
;         _Pragma("unroll") for (int k = 0; k < 4; ++k) ZR[k] = *(const u32x4*)(zp_ + 8 * k); } while (0)
; DI void gdn_scan(const Ctx& c, int bh, const unsigned char* gbase, const float* GL, bf16_t* proj, const float* normw) {
;     ...
;         for (int n = 0; n < 64; n += 2) {
;             LBAR(); if (n > 0) GHELP(n - 1, zB); GZLOAD(zB, n + 1);
;             LBAR(); GHELP(n, zA); { const int nx = n + 2 < 64 ? n + 2 : 63; GZLOAD(zA, nx); }
.LBB0_885:
	v_mov_b64_e32 v[18:19], s[8:9]
	v_mad_i64_i32 v[32:33], s[52:53], v16, s73, v[18:19]
	global_load_dwordx4 v[16:19], v[32:33], off offset:3120
	global_load_dwordx4 v[24:27], v[32:33], off offset:3104
	global_load_dwordx4 v[28:31], v[32:33], off offset:3088
	s_nop 0
	global_load_dwordx4 v[32:35], v[32:33], off offset:3072
	s_waitcnt lgkmcnt(0)
	s_barrier
	s_cmp_eq_u32 s29, 0
	s_mov_b32 s33, 0
	s_cbranch_scc1 .Lnwl_init_0
	v_add_u32_e32 v40, 0x20600, v135
	ds_read_b128 v[66:69], v40
	ds_read_b128 v[52:55], v40 offset:16
	ds_read_b128 v[44:47], v40 offset:32
	ds_read_b128 v[36:39], v40 offset:48
	ds_read_b128 v[70:73], v40 offset:64
	ds_read_b128 v[56:59], v40 offset:80
	ds_read_b128 v[48:51], v40 offset:96
	ds_read_b128 v[40:43], v40 offset:112
	s_waitcnt lgkmcnt(0)
	s_waitcnt vmcnt(8)
	v_and_b32_e32 v75, 0xffff0000, v52
	v_and_b32_e32 v74, 0xffff0000, v66
	v_lshlrev_b32_e32 v61, 16, v52
	v_lshlrev_b32_e32 v60, 16, v66
	v_pk_mul_f32 v[74:75], v[74:75], v[74:75]
	v_and_b32_e32 v77, 0xffff0000, v36
	v_pk_fma_f32 v[60:61], v[60:61], v[60:61], v[74:75]
	v_lshlrev_b32_e32 v75, 16, v53
	v_lshlrev_b32_e32 v74, 16, v67
	v_pk_fma_f32 v[60:61], v[74:75], v[74:75], v[60:61]
	v_and_b32_e32 v75, 0xffff0000, v53
	v_and_b32_e32 v74, 0xffff0000, v67
	v_pk_fma_f32 v[60:61], v[74:75], v[74:75], v[60:61]
	v_lshlrev_b32_e32 v75, 16, v54
	v_lshlrev_b32_e32 v74, 16, v68
	v_pk_fma_f32 v[60:61], v[74:75], v[74:75], v[60:61]
	v_and_b32_e32 v75, 0xffff0000, v54
	v_and_b32_e32 v74, 0xffff0000, v68
	v_pk_fma_f32 v[60:61], v[74:75], v[74:75], v[60:61]
	v_lshlrev_b32_e32 v75, 16, v55
	v_lshlrev_b32_e32 v74, 16, v69
	v_pk_fma_f32 v[60:61], v[74:75], v[74:75], v[60:61]
	v_and_b32_e32 v75, 0xffff0000, v55
	v_and_b32_e32 v74, 0xffff0000, v69
	v_and_b32_e32 v76, 0xffff0000, v44
	v_pk_fma_f32 v[60:61], v[74:75], v[74:75], v[60:61]
	v_lshlrev_b32_e32 v75, 16, v36
	v_lshlrev_b32_e32 v74, 16, v44
	v_pk_mul_f32 v[76:77], v[76:77], v[76:77]
	v_and_b32_e32 v79, 0xffff0000, v56
	v_pk_fma_f32 v[74:75], v[74:75], v[74:75], v[76:77]
	v_lshlrev_b32_e32 v77, 16, v37
	v_lshlrev_b32_e32 v76, 16, v45
	v_pk_fma_f32 v[74:75], v[76:77], v[76:77], v[74:75]
	v_and_b32_e32 v77, 0xffff0000, v37
	v_and_b32_e32 v76, 0xffff0000, v45
	v_pk_fma_f32 v[74:75], v[76:77], v[76:77], v[74:75]
	v_lshlrev_b32_e32 v77, 16, v38
	v_lshlrev_b32_e32 v76, 16, v46
	v_pk_fma_f32 v[74:75], v[76:77], v[76:77], v[74:75]
	v_and_b32_e32 v77, 0xffff0000, v38
	v_and_b32_e32 v76, 0xffff0000, v46
	v_pk_fma_f32 v[74:75], v[76:77], v[76:77], v[74:75]
	v_lshlrev_b32_e32 v77, 16, v39
	v_lshlrev_b32_e32 v76, 16, v47
	v_pk_fma_f32 v[74:75], v[76:77], v[76:77], v[74:75]
	v_and_b32_e32 v77, 0xffff0000, v39
	v_and_b32_e32 v76, 0xffff0000, v47
	v_and_b32_e32 v78, 0xffff0000, v70
	v_pk_fma_f32 v[74:75], v[76:77], v[76:77], v[74:75]
	v_lshlrev_b32_e32 v77, 16, v56
	v_lshlrev_b32_e32 v76, 16, v70
	v_pk_mul_f32 v[78:79], v[78:79], v[78:79]
	v_and_b32_e32 v81, 0xffff0000, v40
	v_pk_fma_f32 v[76:77], v[76:77], v[76:77], v[78:79]
	v_lshlrev_b32_e32 v79, 16, v57
	v_lshlrev_b32_e32 v78, 16, v71
	v_pk_fma_f32 v[76:77], v[78:79], v[78:79], v[76:77]
	v_and_b32_e32 v79, 0xffff0000, v57
	v_and_b32_e32 v78, 0xffff0000, v71
	v_pk_fma_f32 v[76:77], v[78:79], v[78:79], v[76:77]
	v_lshlrev_b32_e32 v79, 16, v58
	v_lshlrev_b32_e32 v78, 16, v72
	v_pk_fma_f32 v[76:77], v[78:79], v[78:79], v[76:77]
	v_and_b32_e32 v79, 0xffff0000, v58
	v_and_b32_e32 v78, 0xffff0000, v72
	v_pk_fma_f32 v[76:77], v[78:79], v[78:79], v[76:77]
	v_lshlrev_b32_e32 v79, 16, v59
	v_lshlrev_b32_e32 v78, 16, v73
	v_pk_fma_f32 v[76:77], v[78:79], v[78:79], v[76:77]
	v_and_b32_e32 v79, 0xffff0000, v59
	v_and_b32_e32 v78, 0xffff0000, v73
	v_and_b32_e32 v80, 0xffff0000, v48
	v_pk_fma_f32 v[76:77], v[78:79], v[78:79], v[76:77]
	v_lshlrev_b32_e32 v79, 16, v40
	v_lshlrev_b32_e32 v78, 16, v48
	v_pk_mul_f32 v[80:81], v[80:81], v[80:81]
	v_add_f32_e32 v60, v60, v61
	v_pk_fma_f32 v[78:79], v[78:79], v[78:79], v[80:81]
	v_lshlrev_b32_e32 v81, 16, v41
	v_lshlrev_b32_e32 v80, 16, v49
	v_pk_fma_f32 v[78:79], v[80:81], v[80:81], v[78:79]
	v_and_b32_e32 v81, 0xffff0000, v41
	v_and_b32_e32 v80, 0xffff0000, v49
	v_pk_fma_f32 v[78:79], v[80:81], v[80:81], v[78:79]
	v_lshlrev_b32_e32 v81, 16, v42
	v_lshlrev_b32_e32 v80, 16, v50
	v_pk_fma_f32 v[78:79], v[80:81], v[80:81], v[78:79]
	v_and_b32_e32 v81, 0xffff0000, v42
	v_and_b32_e32 v80, 0xffff0000, v50
	v_add_f32_e32 v60, v60, v74
	v_pk_fma_f32 v[78:79], v[80:81], v[80:81], v[78:79]
	v_lshlrev_b32_e32 v81, 16, v43
	v_lshlrev_b32_e32 v80, 16, v51
	v_add_f32_e32 v60, v60, v75
	v_pk_fma_f32 v[78:79], v[80:81], v[80:81], v[78:79]
	v_and_b32_e32 v81, 0xffff0000, v43
	v_and_b32_e32 v80, 0xffff0000, v51
	v_add_f32_e32 v60, v60, v76
	v_pk_fma_f32 v[78:79], v[80:81], v[80:81], v[78:79]
	v_add_f32_e32 v60, v60, v77
	v_add_f32_e32 v60, v60, v78
	v_add_f32_e32 v60, v60, v79
	v_fmamk_f32 v60, v60, 0x3c800000, v134
	v_rsq_f32_e32 v62, v60
	v_add_u32_e32 v65, s29, v3
	v_mov_b64_e32 v[60:61], s[8:9]
	v_cndmask_b32_e64 v72, v72, v68, s[6:7]
	v_lshlrev_b32_e32 v68, 16, v20
	v_mad_i64_i32 v[60:61], s[52:53], v65, s73, v[60:61]
	v_cndmask_b32_e64 v65, v73, v69, s[6:7]
	v_and_b32_e32 v69, 0xffff0000, v20
	v_mul_f32_e32 v20, 0xbfb8aa3b, v68
	v_cndmask_b32_e64 v73, v71, v67, s[6:7]
	v_exp_f32_e32 v20, v20
	v_mul_f32_e32 v67, 0xbfb8aa3b, v69
	v_exp_f32_e32 v67, v67
	v_mov_b32_e32 v90, s68
	v_add_f32_e32 v20, 1.0, v20
	v_cndmask_b32_e64 v71, v70, v66, s[6:7]
	v_rcp_f32_e32 v66, v20
	v_add_f32_e32 v20, 1.0, v67
	v_rcp_f32_e32 v67, v20
	v_lshlrev_b32_e32 v70, 16, v71
	v_and_b32_e32 v71, 0xffff0000, v71
	v_pk_mul_f32 v[66:67], v[66:67], v[68:69]
	v_lshlrev_b32_e32 v68, 16, v21
	s_waitcnt lgkmcnt(0)
	v_pk_mul_f32 v[74:75], v[208:209], v[62:63] op_sel_hi:[1,0]
	v_and_b32_e32 v69, 0xffff0000, v21
	v_mul_f32_e32 v20, 0xbfb8aa3b, v68
	v_pk_mul_f32 v[70:71], v[74:75], v[70:71]
	v_exp_f32_e32 v21, v20
	v_mul_f32_e32 v20, 0xbfb8aa3b, v69
	v_pk_mul_f32 v[66:67], v[66:67], v[70:71]
	v_exp_f32_e32 v70, v20
	v_add_f32_e32 v21, 1.0, v21
	v_cvt_pk_bf16_f32 v20, v66, v67
	v_rcp_f32_e32 v66, v21
	v_add_f32_e32 v21, 1.0, v70
	v_rcp_f32_e32 v67, v21
	v_pk_mul_f32 v[76:77], v[210:211], v[62:63] op_sel_hi:[1,0]
	v_lshlrev_b32_e32 v70, 16, v73
	v_and_b32_e32 v71, 0xffff0000, v73
	v_pk_mul_f32 v[66:67], v[66:67], v[68:69]
	v_lshlrev_b32_e32 v68, 16, v22
	v_and_b32_e32 v69, 0xffff0000, v22
	v_mul_f32_e32 v21, 0xbfb8aa3b, v68
	v_pk_mul_f32 v[70:71], v[76:77], v[70:71]
	v_exp_f32_e32 v22, v21
	v_mul_f32_e32 v21, 0xbfb8aa3b, v69
	v_pk_mul_f32 v[66:67], v[66:67], v[70:71]
	v_exp_f32_e32 v70, v21
	v_add_f32_e32 v22, 1.0, v22
	v_cvt_pk_bf16_f32 v21, v66, v67
	v_rcp_f32_e32 v66, v22
	v_add_f32_e32 v22, 1.0, v70
	v_rcp_f32_e32 v67, v22
	v_pk_mul_f32 v[78:79], v[212:213], v[62:63] op_sel_hi:[1,0]
	v_lshlrev_b32_e32 v70, 16, v72
	v_and_b32_e32 v71, 0xffff0000, v72
	v_pk_mul_f32 v[66:67], v[66:67], v[68:69]
	v_lshlrev_b32_e32 v68, 16, v23
	v_and_b32_e32 v69, 0xffff0000, v23
	v_mul_f32_e32 v22, 0xbfb8aa3b, v68
	v_pk_mul_f32 v[70:71], v[78:79], v[70:71]
	v_exp_f32_e32 v23, v22
	v_mul_f32_e32 v22, 0xbfb8aa3b, v69
	v_pk_mul_f32 v[66:67], v[66:67], v[70:71]
	v_exp_f32_e32 v70, v22
	v_cndmask_b32_e64 v58, v58, v54, s[6:7]
	v_lshlrev_b32_e32 v54, 16, v12
	v_add_f32_e32 v23, 1.0, v23
	v_cndmask_b32_e64 v59, v59, v55, s[6:7]
	v_and_b32_e32 v55, 0xffff0000, v12
	v_mul_f32_e32 v12, 0xbfb8aa3b, v54
	v_cvt_pk_bf16_f32 v22, v66, v67
	v_rcp_f32_e32 v66, v23
	v_add_f32_e32 v23, 1.0, v70
	v_lshlrev_b32_e32 v70, 16, v65
	v_and_b32_e32 v71, 0xffff0000, v65
	v_cndmask_b32_e64 v65, v57, v53, s[6:7]
	v_exp_f32_e32 v12, v12
	v_mul_f32_e32 v53, 0xbfb8aa3b, v55
	v_exp_f32_e32 v53, v53
	v_rcp_f32_e32 v67, v23
	v_add_f32_e32 v12, 1.0, v12
	v_pk_mul_f32 v[80:81], v[214:215], v[62:63] op_sel_hi:[1,0]
	v_cndmask_b32_e64 v57, v56, v52, s[6:7]
	v_rcp_f32_e32 v52, v12
	v_add_f32_e32 v12, 1.0, v53
	v_pk_mul_f32 v[70:71], v[80:81], v[70:71]
	v_pk_mul_f32 v[66:67], v[66:67], v[68:69]
	v_rcp_f32_e32 v53, v12
	v_pk_mul_f32 v[66:67], v[66:67], v[70:71]
	v_lshlrev_b32_e32 v56, 16, v57
	v_cvt_pk_bf16_f32 v23, v66, v67
	global_store_dwordx4 v[60:61], v[20:23], off
	v_and_b32_e32 v57, 0xffff0000, v57
	v_pk_mul_f32 v[52:53], v[52:53], v[54:55]
	v_pk_mul_f32 v[22:23], v[216:217], v[62:63] op_sel_hi:[1,0]
	v_pk_mul_f32 v[20:21], v[218:219], v[62:63] op_sel_hi:[1,0]
	v_pk_mul_f32 v[22:23], v[22:23], v[56:57]
	v_and_b32_e32 v55, 0xffff0000, v65
	v_pk_mul_f32 v[22:23], v[52:53], v[22:23]
	v_lshlrev_b32_e32 v52, 16, v13
	v_and_b32_e32 v53, 0xffff0000, v13
	v_mul_f32_e32 v12, 0xbfb8aa3b, v52
	v_exp_f32_e32 v13, v12
	v_mul_f32_e32 v12, 0xbfb8aa3b, v53
	v_exp_f32_e32 v54, v12
	v_cvt_pk_bf16_f32 v12, v22, v23
	v_add_f32_e32 v13, 1.0, v13
	v_rcp_f32_e32 v22, v13
	v_add_f32_e32 v13, 1.0, v54
	v_rcp_f32_e32 v23, v13
	v_lshlrev_b32_e32 v54, 16, v65
	v_pk_mul_f32 v[20:21], v[20:21], v[54:55]
	v_pk_mul_f32 v[68:69], v[220:221], v[62:63] op_sel_hi:[1,0]
	v_pk_mul_f32 v[22:23], v[22:23], v[52:53]
	v_and_b32_e32 v53, 0xffff0000, v58
	v_pk_mul_f32 v[20:21], v[22:23], v[20:21]
	v_lshlrev_b32_e32 v22, 16, v14
	v_and_b32_e32 v23, 0xffff0000, v14
	v_mul_f32_e32 v13, 0xbfb8aa3b, v22
	v_exp_f32_e32 v14, v13
	v_mul_f32_e32 v13, 0xbfb8aa3b, v23
	v_exp_f32_e32 v52, v13
	v_cvt_pk_bf16_f32 v13, v20, v21
	v_add_f32_e32 v14, 1.0, v14
	v_rcp_f32_e32 v20, v14
	v_add_f32_e32 v14, 1.0, v52
	v_rcp_f32_e32 v21, v14
	v_lshlrev_b32_e32 v52, 16, v58
	v_pk_mul_f32 v[52:53], v[68:69], v[52:53]
	v_pk_mul_f32 v[66:67], v[222:223], v[62:63] op_sel_hi:[1,0]
	v_pk_mul_f32 v[20:21], v[20:21], v[22:23]
	v_lshlrev_b32_e32 v22, 16, v15
	v_and_b32_e32 v23, 0xffff0000, v15
	v_mul_f32_e32 v14, 0xbfb8aa3b, v22
	v_exp_f32_e32 v15, v14
	v_mul_f32_e32 v14, 0xbfb8aa3b, v23
	v_pk_mul_f32 v[20:21], v[20:21], v[52:53]
	v_exp_f32_e32 v52, v14
	v_add_f32_e32 v15, 1.0, v15
	v_cvt_pk_bf16_f32 v14, v20, v21
	v_rcp_f32_e32 v20, v15
	v_add_f32_e32 v15, 1.0, v52
	v_rcp_f32_e32 v21, v15
	v_lshlrev_b32_e32 v52, 16, v59
	v_and_b32_e32 v53, 0xffff0000, v59
	v_pk_mul_f32 v[52:53], v[66:67], v[52:53]
	v_pk_mul_f32 v[54:55], v[20:21], v[22:23]
	v_pk_mul_f32 v[56:57], v[54:55], v[52:53]
	v_cndmask_b32_e64 v50, v50, v46, s[6:7]
	v_lshlrev_b32_e32 v46, 16, v8
	v_cvt_pk_bf16_f32 v15, v56, v57
	v_cndmask_b32_e64 v51, v51, v47, s[6:7]
	v_and_b32_e32 v47, 0xffff0000, v8
	v_mul_f32_e32 v8, 0xbfb8aa3b, v46
	global_store_dwordx4 v[60:61], v[12:15], off offset:16
	v_exp_f32_e32 v8, v8
	v_cndmask_b32_e64 v41, v41, v37, s[6:7]
	s_waitcnt lgkmcnt(0)
; #define LBAR() do { asm volatile("s_waitcnt lgkmcnt(0)" ::: "memory"); __builtin_amdgcn_s_barrier(); asm volatile("" ::: "memory"); } while (0)
; #define GZLOAD(ZR, chunk) do { const bf16_t* zp_ = proj + (size_t)(b * SEQ + (chunk) * 64 + lane) * NINP + C_GZ + h * 64 + 32 * hc; \
;         _Pragma("unroll") for (int k = 0; k < 4; ++k) ZR[k] = *(const u32x4*)(zp_ + 8 * k); } while (0)
; DI void gdn_scan(const Ctx& c, int bh, const unsigned char* gbase, const float* GL, bf16_t* proj, const float* normw) {
;     ...
;         for (int n = 0; n < 64; n += 2) {
;             LBAR(); if (n > 0) GHELP(n - 1, zB); GZLOAD(zB, n + 1);
;             LBAR(); GHELP(n, zA); { const int nx = n + 2 < 64 ? n + 2 : 63; GZLOAD(zA, nx); }
	v_pk_mul_f32 v[12:13], v[226:227], v[62:63] op_sel_hi:[1,0]
	v_pk_mul_f32 v[22:23], v[228:229], v[62:63] op_sel_hi:[1,0]
	v_cndmask_b32_e64 v52, v49, v45, s[6:7]
	v_mul_f32_e32 v45, 0xbfb8aa3b, v47
	v_exp_f32_e32 v45, v45
	v_add_f32_e32 v8, 1.0, v8
	v_cndmask_b32_e64 v49, v48, v44, s[6:7]
	v_rcp_f32_e32 v44, v8
	v_add_f32_e32 v8, 1.0, v45
	v_rcp_f32_e32 v45, v8
	v_pk_mul_f32 v[14:15], v[224:225], v[62:63] op_sel_hi:[1,0]
	v_lshlrev_b32_e32 v48, 16, v49
	v_and_b32_e32 v49, 0xffff0000, v49
	v_pk_mul_f32 v[14:15], v[14:15], v[48:49]
	v_pk_mul_f32 v[44:45], v[44:45], v[46:47]
	v_and_b32_e32 v47, 0xffff0000, v52
	v_pk_mul_f32 v[14:15], v[44:45], v[14:15]
	v_lshlrev_b32_e32 v44, 16, v9
	v_and_b32_e32 v45, 0xffff0000, v9
	v_mul_f32_e32 v8, 0xbfb8aa3b, v44
	v_exp_f32_e32 v9, v8
	v_mul_f32_e32 v8, 0xbfb8aa3b, v45
	v_exp_f32_e32 v46, v8
	v_cvt_pk_bf16_f32 v8, v14, v15
	v_add_f32_e32 v9, 1.0, v9
	v_rcp_f32_e32 v14, v9
	v_add_f32_e32 v9, 1.0, v46
	v_rcp_f32_e32 v15, v9
	v_lshlrev_b32_e32 v46, 16, v52
	v_pk_mul_f32 v[12:13], v[12:13], v[46:47]
	v_pk_mul_f32 v[20:21], v[230:231], v[62:63] op_sel_hi:[1,0]
	v_pk_mul_f32 v[14:15], v[14:15], v[44:45]
	v_and_b32_e32 v45, 0xffff0000, v50
	v_pk_mul_f32 v[12:13], v[14:15], v[12:13]
	v_lshlrev_b32_e32 v14, 16, v10
	v_and_b32_e32 v15, 0xffff0000, v10
	v_mul_f32_e32 v9, 0xbfb8aa3b, v14
	v_exp_f32_e32 v10, v9
	v_mul_f32_e32 v9, 0xbfb8aa3b, v15
	v_exp_f32_e32 v44, v9
	v_cvt_pk_bf16_f32 v9, v12, v13
	v_add_f32_e32 v10, 1.0, v10
	v_rcp_f32_e32 v12, v10
	v_add_f32_e32 v10, 1.0, v44
	v_rcp_f32_e32 v13, v10
	v_lshlrev_b32_e32 v44, 16, v50
	v_pk_mul_f32 v[22:23], v[22:23], v[44:45]
	v_cndmask_b32_e64 v37, v40, v36, s[6:7]
	v_pk_mul_f32 v[12:13], v[12:13], v[14:15]
	v_lshlrev_b32_e32 v14, 16, v11
	v_and_b32_e32 v15, 0xffff0000, v11
	v_mul_f32_e32 v10, 0xbfb8aa3b, v14
	v_exp_f32_e32 v11, v10
	v_mul_f32_e32 v10, 0xbfb8aa3b, v15
	v_pk_mul_f32 v[12:13], v[12:13], v[22:23]
	v_exp_f32_e32 v22, v10
	v_add_f32_e32 v11, 1.0, v11
	v_cvt_pk_bf16_f32 v10, v12, v13
	v_rcp_f32_e32 v12, v11
	v_add_f32_e32 v11, 1.0, v22
	v_rcp_f32_e32 v13, v11
	v_lshlrev_b32_e32 v22, 16, v51
	v_and_b32_e32 v23, 0xffff0000, v51
	v_pk_mul_f32 v[20:21], v[20:21], v[22:23]
	v_pk_mul_f32 v[22:23], v[12:13], v[14:15]
	v_pk_mul_f32 v[44:45], v[22:23], v[20:21]
	v_cvt_pk_bf16_f32 v11, v44, v45
	global_store_dwordx4 v[60:61], v[8:11], off offset:32
	v_lshlrev_b32_e32 v36, 16, v37
	v_and_b32_e32 v37, 0xffff0000, v37
	s_waitcnt lgkmcnt(0)
	v_pk_mul_f32 v[8:9], v[234:235], v[62:63] op_sel_hi:[1,0]
	v_pk_mul_f32 v[14:15], v[236:237], v[62:63] op_sel_hi:[1,0]
	v_lshlrev_b32_e32 v20, 16, v4
	v_and_b32_e32 v21, 0xffff0000, v4
	v_mul_f32_e32 v4, 0xbfb8aa3b, v20
	v_pk_mul_f32 v[10:11], v[232:233], v[62:63] op_sel_hi:[1,0]
	v_pk_mul_f32 v[12:13], v[238:239], v[62:63] op_sel_hi:[1,0]
	v_exp_f32_e32 v4, v4
	v_mul_f32_e32 v22, 0xbfb8aa3b, v21
	v_exp_f32_e32 v23, v22
	v_pk_mul_f32 v[10:11], v[10:11], v[36:37]
	v_add_f32_e32 v4, 1.0, v4
	v_rcp_f32_e32 v22, v4
	v_add_f32_e32 v4, 1.0, v23
	v_rcp_f32_e32 v23, v4
	v_cndmask_b32_e64 v38, v42, v38, s[6:7]
	v_cndmask_b32_e64 v39, v43, v39, s[6:7]
	s_mov_b32 s33, s29
	v_pk_mul_f32 v[20:21], v[22:23], v[20:21]
	v_and_b32_e32 v23, 0xffff0000, v41
	v_pk_mul_f32 v[10:11], v[20:21], v[10:11]
	v_lshlrev_b32_e32 v20, 16, v5
	v_and_b32_e32 v21, 0xffff0000, v5
	v_mul_f32_e32 v4, 0xbfb8aa3b, v20
	v_exp_f32_e32 v5, v4
	v_mul_f32_e32 v4, 0xbfb8aa3b, v21
	v_exp_f32_e32 v22, v4
	v_cvt_pk_bf16_f32 v4, v10, v11
	v_add_f32_e32 v5, 1.0, v5
	v_rcp_f32_e32 v10, v5
	v_add_f32_e32 v5, 1.0, v22
	v_rcp_f32_e32 v11, v5
	v_lshlrev_b32_e32 v22, 16, v41
	v_pk_mul_f32 v[8:9], v[8:9], v[22:23]
	v_pk_mul_f32 v[10:11], v[10:11], v[20:21]
	s_nop 0
	v_pk_mul_f32 v[8:9], v[10:11], v[8:9]
	v_lshlrev_b32_e32 v10, 16, v6
	v_and_b32_e32 v11, 0xffff0000, v6
	v_mul_f32_e32 v5, 0xbfb8aa3b, v10
	v_exp_f32_e32 v6, v5
	v_mul_f32_e32 v5, 0xbfb8aa3b, v11
	v_exp_f32_e32 v20, v5
	v_cvt_pk_bf16_f32 v5, v8, v9
	v_add_f32_e32 v6, 1.0, v6
	v_rcp_f32_e32 v8, v6
	v_add_f32_e32 v6, 1.0, v20
	v_rcp_f32_e32 v9, v6
	v_lshlrev_b32_e32 v20, 16, v38
	v_and_b32_e32 v21, 0xffff0000, v38
	v_pk_mul_f32 v[14:15], v[14:15], v[20:21]
	v_pk_mul_f32 v[8:9], v[8:9], v[10:11]
	v_lshlrev_b32_e32 v10, 16, v7
	v_and_b32_e32 v11, 0xffff0000, v7
	v_mul_f32_e32 v6, 0xbfb8aa3b, v10
	v_exp_f32_e32 v7, v6
	v_mul_f32_e32 v6, 0xbfb8aa3b, v11
	v_pk_mul_f32 v[8:9], v[8:9], v[14:15]
	v_exp_f32_e32 v14, v6
	v_add_f32_e32 v7, 1.0, v7
	v_cvt_pk_bf16_f32 v6, v8, v9
	v_rcp_f32_e32 v8, v7
	v_add_f32_e32 v7, 1.0, v14
	v_rcp_f32_e32 v9, v7
	v_lshlrev_b32_e32 v14, 16, v39
	v_and_b32_e32 v15, 0xffff0000, v39
	v_pk_mul_f32 v[12:13], v[12:13], v[14:15]
	v_pk_mul_f32 v[8:9], v[8:9], v[10:11]
	s_nop 0
	v_pk_mul_f32 v[8:9], v[8:9], v[12:13]
	s_nop 0
	v_cvt_pk_bf16_f32 v7, v8, v9
	global_store_dwordx4 v[60:61], v[4:7], off offset:48
	s_branch .LBB0_884
.Lnwl_init_0:
	v_mov_b32_e32 v240, s68
	ds_read_b128 v[208:211], v240
	ds_read_b128 v[212:215], v240 offset:16
	ds_read_b128 v[216:219], v240 offset:32
	ds_read_b128 v[220:223], v240 offset:48
	ds_read_b128 v[224:227], v240 offset:64
	ds_read_b128 v[228:231], v240 offset:80
	ds_read_b128 v[232:235], v240 offset:96
	ds_read_b128 v[236:239], v240 offset:112
	s_branch .LBB0_884

; DI float fexp2(float x) { return __builtin_amdgcn_exp2f(x); }
; DI float half_max(float v) { const unsigned u = __float_as_uint(v); auto rr = __builtin_amdgcn_permlane32_swap(u, u, false, false); return fmaxf(__uint_as_float(rr[0]), __uint_as_float(rr[1])); }
; template <int MODE>
; DI void attn_unit(const Ctx& c, int bh, int qb, const bf16_t* Qp, int qpitch, const bf16_t* Kp, int kpitch, const bf16_t* VTp, bf16_t* Op, int opitch) {
;     ...
;                 float mx = fmaxf(s0[0], s1[0]);
; #pragma unroll
;                 for (int r = 1; r < 16; ++r) mx = fmaxf(mx, fmaxf(s0[r], s1[r]));
;                 mx = half_max(mx);
;                 if (__any(mx > mrun)) {
;                     const float mn_ = fmaxf(mrun, mx), al = fexp2(mrun - mn_); mrun = mn_; lrun *= al;
; #pragma unroll
;                     for (int r = 0; r < 16; ++r) { o[0][r] *= al; o[1][r] *= al; } }
.LBB0_926:
	s_nop 8
	v_max_f32_e32 v2, v53, v37
	v_max_f32_e32 v231, v54, v38
	v_max3_f32 v2, v52, v36, v2
	v_max_f32_e32 v232, v55, v39
	v_max3_f32 v2, v2, v231, v232
	v_max_f32_e32 v231, v56, v40
	v_max_f32_e32 v232, v57, v41
	v_max3_f32 v2, v2, v231, v232
	v_max_f32_e32 v231, v58, v42
	v_max_f32_e32 v232, v59, v43
	v_max3_f32 v2, v2, v231, v232
	v_max_f32_e32 v231, v60, v44
	v_max_f32_e32 v232, v61, v45
	v_max3_f32 v2, v2, v231, v232
	v_max_f32_e32 v231, v62, v46
	v_max_f32_e32 v232, v63, v47
	v_max3_f32 v2, v2, v231, v232
	v_max_f32_e32 v231, v64, v48
	v_max_f32_e32 v232, v65, v49
	v_max3_f32 v2, v2, v231, v232
	v_max_f32_e32 v231, v66, v50
	v_max_f32_e32 v232, v67, v51
	v_max3_f32 v2, v2, v231, v232
	v_mov_b32_e32 v231, v2
	s_nop 1
	v_permlane32_swap_b32_e32 v2, v231
	v_max_f32_e32 v2, v2, v231
	v_cmp_gt_f32_e32 vcc, v2, v189
	s_cbranch_vccz .LBB0_921
	v_max_f32_e32 v231, v189, v2
	v_sub_f32_e32 v2, v189, v231
	v_exp_f32_e32 v2, v2
	v_mov_b32_e32 v189, v231
	v_pk_mul_f32 v[34:35], v[34:35], v[2:3] op_sel_hi:[1,0]
	v_pk_mul_f32 v[32:33], v[32:33], v[2:3] op_sel_hi:[1,0]
	v_pk_mul_f32 v[30:31], v[30:31], v[2:3] op_sel_hi:[1,0]
	v_pk_mul_f32 v[28:29], v[28:29], v[2:3] op_sel_hi:[1,0]
	v_pk_mul_f32 v[26:27], v[26:27], v[2:3] op_sel_hi:[1,0]
	v_pk_mul_f32 v[24:25], v[24:25], v[2:3] op_sel_hi:[1,0]
	v_pk_mul_f32 v[22:23], v[22:23], v[2:3] op_sel_hi:[1,0]
	v_pk_mul_f32 v[20:21], v[20:21], v[2:3] op_sel_hi:[1,0]
	v_pk_mul_f32 v[18:19], v[18:19], v[2:3] op_sel_hi:[1,0]
	v_pk_mul_f32 v[16:17], v[16:17], v[2:3] op_sel_hi:[1,0]
	v_pk_mul_f32 v[14:15], v[14:15], v[2:3] op_sel_hi:[1,0]
	v_pk_mul_f32 v[12:13], v[12:13], v[2:3] op_sel_hi:[1,0]
	v_pk_mul_f32 v[10:11], v[10:11], v[2:3] op_sel_hi:[1,0]
	v_pk_mul_f32 v[8:9], v[8:9], v[2:3] op_sel_hi:[1,0]
	v_pk_mul_f32 v[6:7], v[6:7], v[2:3] op_sel_hi:[1,0]
	v_pk_mul_f32 v[4:5], v[4:5], v[2:3] op_sel_hi:[1,0]
	v_mul_f32_e32 v187, v187, v2
	s_branch .LBB0_921

; #define LBAR() do { asm volatile("s_waitcnt lgkmcnt(0)" ::: "memory"); __builtin_amdgcn_s_barrier(); asm volatile("" ::: "memory"); } while (0)
; DI void gdn_scan(const Ctx& c, int bh, const unsigned char* gbase, const float* GL, bf16_t* proj, const float* normw) {
;     ...
;         LBAR();
;         GHELP(63, zB);
.LBB0_2172:
	s_waitcnt lgkmcnt(0)
	s_barrier
	s_waitcnt vmcnt(0)
	v_add_u32_e32 v3, 0x20600, v135
	ds_read_b128 v[48:51], v3
	ds_read_b128 v[36:39], v3 offset:16
	ds_read_b128 v[28:31], v3 offset:32
	ds_read_b128 v[16:19], v3 offset:48
	ds_read_b128 v[52:55], v3 offset:64
	ds_read_b128 v[40:43], v3 offset:80
	ds_read_b128 v[32:35], v3 offset:96
	ds_read_b128 v[24:27], v3 offset:112
	s_waitcnt lgkmcnt(6)
	v_and_b32_e32 v47, 0xffff0000, v36
	v_and_b32_e32 v46, 0xffff0000, v48
	v_lshlrev_b32_e32 v45, 16, v36
	v_lshlrev_b32_e32 v44, 16, v48
	v_pk_mul_f32 v[46:47], v[46:47], v[46:47]
	s_waitcnt lgkmcnt(4)
	v_and_b32_e32 v57, 0xffff0000, v16
	v_pk_fma_f32 v[44:45], v[44:45], v[44:45], v[46:47]
	v_lshlrev_b32_e32 v47, 16, v37
	v_lshlrev_b32_e32 v46, 16, v49
	v_pk_fma_f32 v[44:45], v[46:47], v[46:47], v[44:45]
	v_and_b32_e32 v47, 0xffff0000, v37
	v_and_b32_e32 v46, 0xffff0000, v49
	v_pk_fma_f32 v[44:45], v[46:47], v[46:47], v[44:45]
	v_lshlrev_b32_e32 v47, 16, v38
	v_lshlrev_b32_e32 v46, 16, v50
	v_pk_fma_f32 v[44:45], v[46:47], v[46:47], v[44:45]
	v_and_b32_e32 v47, 0xffff0000, v38
	v_and_b32_e32 v46, 0xffff0000, v50
	v_pk_fma_f32 v[44:45], v[46:47], v[46:47], v[44:45]
	v_lshlrev_b32_e32 v47, 16, v39
	v_lshlrev_b32_e32 v46, 16, v51
	v_pk_fma_f32 v[44:45], v[46:47], v[46:47], v[44:45]
	v_and_b32_e32 v47, 0xffff0000, v39
	v_and_b32_e32 v46, 0xffff0000, v51
	v_and_b32_e32 v56, 0xffff0000, v28
	v_pk_fma_f32 v[44:45], v[46:47], v[46:47], v[44:45]
	v_lshlrev_b32_e32 v47, 16, v16
	v_lshlrev_b32_e32 v46, 16, v28
	v_pk_mul_f32 v[56:57], v[56:57], v[56:57]
	s_waitcnt lgkmcnt(2)
	v_and_b32_e32 v59, 0xffff0000, v40
	v_pk_fma_f32 v[46:47], v[46:47], v[46:47], v[56:57]
	v_lshlrev_b32_e32 v57, 16, v17
	v_lshlrev_b32_e32 v56, 16, v29
	v_pk_fma_f32 v[46:47], v[56:57], v[56:57], v[46:47]
	v_and_b32_e32 v57, 0xffff0000, v17
	v_and_b32_e32 v56, 0xffff0000, v29
	v_pk_fma_f32 v[46:47], v[56:57], v[56:57], v[46:47]
	v_lshlrev_b32_e32 v57, 16, v18
	v_lshlrev_b32_e32 v56, 16, v30
	v_pk_fma_f32 v[46:47], v[56:57], v[56:57], v[46:47]
	v_and_b32_e32 v57, 0xffff0000, v18
	v_and_b32_e32 v56, 0xffff0000, v30
	v_pk_fma_f32 v[46:47], v[56:57], v[56:57], v[46:47]
	v_lshlrev_b32_e32 v57, 16, v19
	v_lshlrev_b32_e32 v56, 16, v31
	v_pk_fma_f32 v[46:47], v[56:57], v[56:57], v[46:47]
	v_and_b32_e32 v57, 0xffff0000, v19
	v_and_b32_e32 v56, 0xffff0000, v31
	v_and_b32_e32 v58, 0xffff0000, v52
	v_pk_fma_f32 v[46:47], v[56:57], v[56:57], v[46:47]
	v_lshlrev_b32_e32 v57, 16, v40
	v_lshlrev_b32_e32 v56, 16, v52
	v_pk_mul_f32 v[58:59], v[58:59], v[58:59]
	s_waitcnt lgkmcnt(0)
	v_and_b32_e32 v61, 0xffff0000, v24
	v_pk_fma_f32 v[56:57], v[56:57], v[56:57], v[58:59]
	v_lshlrev_b32_e32 v59, 16, v41
	v_lshlrev_b32_e32 v58, 16, v53
	v_pk_fma_f32 v[56:57], v[58:59], v[58:59], v[56:57]
	v_and_b32_e32 v59, 0xffff0000, v41
	v_and_b32_e32 v58, 0xffff0000, v53
	v_pk_fma_f32 v[56:57], v[58:59], v[58:59], v[56:57]
	v_lshlrev_b32_e32 v59, 16, v42
	v_lshlrev_b32_e32 v58, 16, v54
	v_pk_fma_f32 v[56:57], v[58:59], v[58:59], v[56:57]
	v_and_b32_e32 v59, 0xffff0000, v42
	v_and_b32_e32 v58, 0xffff0000, v54
	v_pk_fma_f32 v[56:57], v[58:59], v[58:59], v[56:57]
	v_lshlrev_b32_e32 v59, 16, v43
	v_lshlrev_b32_e32 v58, 16, v55
	v_pk_fma_f32 v[56:57], v[58:59], v[58:59], v[56:57]
	v_and_b32_e32 v59, 0xffff0000, v43
	v_and_b32_e32 v58, 0xffff0000, v55
	v_and_b32_e32 v60, 0xffff0000, v32
	v_pk_fma_f32 v[56:57], v[58:59], v[58:59], v[56:57]
	v_lshlrev_b32_e32 v59, 16, v24
	v_lshlrev_b32_e32 v58, 16, v32
	v_pk_mul_f32 v[60:61], v[60:61], v[60:61]
	v_add_f32_e32 v3, v44, v45
	v_pk_fma_f32 v[58:59], v[58:59], v[58:59], v[60:61]
	v_lshlrev_b32_e32 v61, 16, v25
	v_lshlrev_b32_e32 v60, 16, v33
	v_pk_fma_f32 v[58:59], v[60:61], v[60:61], v[58:59]
	v_and_b32_e32 v61, 0xffff0000, v25
	v_and_b32_e32 v60, 0xffff0000, v33
	v_pk_fma_f32 v[58:59], v[60:61], v[60:61], v[58:59]
	v_lshlrev_b32_e32 v61, 16, v26
	v_lshlrev_b32_e32 v60, 16, v34
	v_pk_fma_f32 v[58:59], v[60:61], v[60:61], v[58:59]
	v_and_b32_e32 v61, 0xffff0000, v26
	v_and_b32_e32 v60, 0xffff0000, v34
	v_add_f32_e32 v3, v3, v46
	v_pk_fma_f32 v[58:59], v[60:61], v[60:61], v[58:59]
	v_lshlrev_b32_e32 v61, 16, v27
	v_lshlrev_b32_e32 v60, 16, v35
	v_add_f32_e32 v3, v3, v47
	v_pk_fma_f32 v[58:59], v[60:61], v[60:61], v[58:59]
	v_and_b32_e32 v61, 0xffff0000, v27
	v_and_b32_e32 v60, 0xffff0000, v35
	v_add_f32_e32 v3, v3, v56
	v_pk_fma_f32 v[58:59], v[60:61], v[60:61], v[58:59]
	v_add_f32_e32 v3, v3, v57
	v_add_f32_e32 v3, v3, v58
	v_add_f32_e32 v3, v3, v59
	v_fmamk_f32 v3, v3, 0x3c800000, v134
	v_rsq_f32_e32 v46, v3
	v_or_b32_e32 v3, s12, v132
	v_mov_b64_e32 v[44:45], s[2:3]
	v_mad_i64_i32 v[44:45], s[8:9], v3, s79, v[44:45]
	v_mov_b32_e32 v3, s75
	v_cndmask_b32_e64 v54, v54, v50, s[6:7]
	v_lshlrev_b32_e32 v50, 16, v20
	s_waitcnt lgkmcnt(0)
	v_pk_mul_f32 v[62:63], v[214:215], v[46:47] op_sel_hi:[1,0]
	v_pk_mul_f32 v[58:59], v[210:211], v[46:47] op_sel_hi:[1,0]
	v_pk_mul_f32 v[56:57], v[208:209], v[46:47] op_sel_hi:[1,0]
	v_pk_mul_f32 v[60:61], v[212:213], v[46:47] op_sel_hi:[1,0]
	v_cndmask_b32_e64 v47, v55, v51, s[6:7]
	v_and_b32_e32 v51, 0xffff0000, v20
	v_mul_f32_e32 v20, 0xbfb8aa3b, v50
	v_cndmask_b32_e64 v55, v53, v49, s[6:7]
	v_exp_f32_e32 v20, v20
	v_mul_f32_e32 v49, 0xbfb8aa3b, v51
	v_exp_f32_e32 v49, v49
	v_cndmask_b32_e64 v53, v52, v48, s[6:7]
	v_add_f32_e32 v20, 1.0, v20
	v_rcp_f32_e32 v48, v20
	v_add_f32_e32 v20, 1.0, v49
	v_rcp_f32_e32 v49, v20
	v_lshlrev_b32_e32 v52, 16, v53
	v_and_b32_e32 v53, 0xffff0000, v53
	v_pk_mul_f32 v[52:53], v[56:57], v[52:53]
	v_pk_mul_f32 v[48:49], v[48:49], v[50:51]
	v_lshlrev_b32_e32 v50, 16, v21
	v_and_b32_e32 v51, 0xffff0000, v21
	v_mul_f32_e32 v20, 0xbfb8aa3b, v50
	v_exp_f32_e32 v21, v20
	v_mul_f32_e32 v20, 0xbfb8aa3b, v51
	v_pk_mul_f32 v[48:49], v[48:49], v[52:53]
	v_exp_f32_e32 v52, v20
	v_add_f32_e32 v21, 1.0, v21
	v_cvt_pk_bf16_f32 v20, v48, v49
	v_rcp_f32_e32 v48, v21
	v_add_f32_e32 v21, 1.0, v52
	v_rcp_f32_e32 v49, v21
	v_lshlrev_b32_e32 v52, 16, v55
	v_and_b32_e32 v53, 0xffff0000, v55
	v_pk_mul_f32 v[52:53], v[58:59], v[52:53]
	v_pk_mul_f32 v[48:49], v[48:49], v[50:51]
	v_lshlrev_b32_e32 v50, 16, v22
	v_and_b32_e32 v51, 0xffff0000, v22
	v_mul_f32_e32 v21, 0xbfb8aa3b, v50
	v_exp_f32_e32 v22, v21
	v_mul_f32_e32 v21, 0xbfb8aa3b, v51
	v_pk_mul_f32 v[48:49], v[48:49], v[52:53]
	v_exp_f32_e32 v52, v21
	v_add_f32_e32 v22, 1.0, v22
	v_cvt_pk_bf16_f32 v21, v48, v49
	v_rcp_f32_e32 v48, v22
	v_add_f32_e32 v22, 1.0, v52
	v_rcp_f32_e32 v49, v22
	v_lshlrev_b32_e32 v52, 16, v54
	v_and_b32_e32 v53, 0xffff0000, v54
	v_pk_mul_f32 v[52:53], v[60:61], v[52:53]
	v_pk_mul_f32 v[48:49], v[48:49], v[50:51]
	v_lshlrev_b32_e32 v50, 16, v23
	v_and_b32_e32 v51, 0xffff0000, v23
	v_mul_f32_e32 v22, 0xbfb8aa3b, v50
	v_exp_f32_e32 v23, v22
	v_mul_f32_e32 v22, 0xbfb8aa3b, v51
	v_pk_mul_f32 v[48:49], v[48:49], v[52:53]
	v_exp_f32_e32 v52, v22
	v_add_f32_e32 v23, 1.0, v23
	v_cvt_pk_bf16_f32 v22, v48, v49
	v_rcp_f32_e32 v48, v23
	v_add_f32_e32 v23, 1.0, v52
	v_rcp_f32_e32 v49, v23
	v_lshlrev_b32_e32 v52, 16, v47
	v_and_b32_e32 v53, 0xffff0000, v47
	s_lshl_b32 s12, s64, 1
	v_pk_mul_f32 v[52:53], v[62:63], v[52:53]
	v_pk_mul_f32 v[48:49], v[48:49], v[50:51]
	v_lshl_add_u64 v[44:45], v[44:45], 0, s[12:13]
	v_pk_mul_f32 v[48:49], v[48:49], v[52:53]
	v_cndmask_b32_e64 v42, v42, v38, s[6:7]
	v_lshlrev_b32_e32 v38, 16, v12
	v_lshl_add_u64 v[44:45], s[20:21], 1, v[44:45]
	v_cvt_pk_bf16_f32 v23, v48, v49
	v_cndmask_b32_e64 v43, v43, v39, s[6:7]
	v_and_b32_e32 v39, 0xffff0000, v12
	v_mul_f32_e32 v12, 0xbfb8aa3b, v38
	global_store_dwordx4 v[44:45], v[20:23], off
	s_waitcnt lgkmcnt(0)
	v_pk_mul_f32 v[48:49], v[222:223], v[46:47] op_sel_hi:[1,0]
	v_pk_mul_f32 v[50:51], v[220:221], v[46:47] op_sel_hi:[1,0]
	v_pk_mul_f32 v[20:21], v[218:219], v[46:47] op_sel_hi:[1,0]
	v_pk_mul_f32 v[22:23], v[216:217], v[46:47] op_sel_hi:[1,0]
	v_cndmask_b32_e64 v47, v41, v37, s[6:7]
	v_exp_f32_e32 v12, v12
	v_mul_f32_e32 v37, 0xbfb8aa3b, v39
	v_exp_f32_e32 v37, v37
	v_cndmask_b32_e64 v41, v40, v36, s[6:7]
	v_add_f32_e32 v12, 1.0, v12
	v_rcp_f32_e32 v36, v12
	v_add_f32_e32 v12, 1.0, v37
	v_rcp_f32_e32 v37, v12
	v_lshlrev_b32_e32 v40, 16, v41
	v_and_b32_e32 v41, 0xffff0000, v41
	v_pk_mul_f32 v[22:23], v[22:23], v[40:41]
	v_pk_mul_f32 v[36:37], v[36:37], v[38:39]
	v_and_b32_e32 v39, 0xffff0000, v47
	v_pk_mul_f32 v[22:23], v[36:37], v[22:23]
	v_lshlrev_b32_e32 v36, 16, v13
	v_and_b32_e32 v37, 0xffff0000, v13
	v_mul_f32_e32 v12, 0xbfb8aa3b, v36
	v_exp_f32_e32 v13, v12
	v_mul_f32_e32 v12, 0xbfb8aa3b, v37
	v_exp_f32_e32 v38, v12
	v_cvt_pk_bf16_f32 v12, v22, v23
	v_add_f32_e32 v13, 1.0, v13
	v_rcp_f32_e32 v22, v13
	v_add_f32_e32 v13, 1.0, v38
	v_rcp_f32_e32 v23, v13
	v_lshlrev_b32_e32 v38, 16, v47
	v_pk_mul_f32 v[20:21], v[20:21], v[38:39]
	v_cndmask_b32_e64 v34, v34, v30, s[6:7]
	v_pk_mul_f32 v[22:23], v[22:23], v[36:37]
	v_and_b32_e32 v37, 0xffff0000, v42
	v_pk_mul_f32 v[20:21], v[22:23], v[20:21]
	v_lshlrev_b32_e32 v22, 16, v14
	v_and_b32_e32 v23, 0xffff0000, v14
	v_mul_f32_e32 v13, 0xbfb8aa3b, v22
	v_exp_f32_e32 v14, v13
	v_mul_f32_e32 v13, 0xbfb8aa3b, v23
	v_exp_f32_e32 v36, v13
	v_cvt_pk_bf16_f32 v13, v20, v21
	v_add_f32_e32 v14, 1.0, v14
	v_rcp_f32_e32 v20, v14
	v_add_f32_e32 v14, 1.0, v36
	v_rcp_f32_e32 v21, v14
	v_lshlrev_b32_e32 v36, 16, v42
	v_pk_mul_f32 v[36:37], v[50:51], v[36:37]
	v_lshlrev_b32_e32 v30, 16, v8
	v_pk_mul_f32 v[20:21], v[20:21], v[22:23]
	v_lshlrev_b32_e32 v22, 16, v15
	v_and_b32_e32 v23, 0xffff0000, v15
	v_mul_f32_e32 v14, 0xbfb8aa3b, v22
	v_exp_f32_e32 v15, v14
	v_mul_f32_e32 v14, 0xbfb8aa3b, v23
	v_pk_mul_f32 v[20:21], v[20:21], v[36:37]
	v_exp_f32_e32 v36, v14
	v_add_f32_e32 v15, 1.0, v15
	v_cvt_pk_bf16_f32 v14, v20, v21
	v_rcp_f32_e32 v20, v15
	v_add_f32_e32 v15, 1.0, v36
	v_rcp_f32_e32 v21, v15
	v_lshlrev_b32_e32 v36, 16, v43
	v_and_b32_e32 v37, 0xffff0000, v43
	v_pk_mul_f32 v[36:37], v[48:49], v[36:37]
	v_pk_mul_f32 v[38:39], v[20:21], v[22:23]
	v_pk_mul_f32 v[40:41], v[38:39], v[36:37]
	v_cvt_pk_bf16_f32 v15, v40, v41
	v_cndmask_b32_e64 v35, v35, v31, s[6:7]
	v_and_b32_e32 v31, 0xffff0000, v8
	v_mul_f32_e32 v8, 0xbfb8aa3b, v30
	global_store_dwordx4 v[44:45], v[12:15], off offset:16
	v_exp_f32_e32 v8, v8
	s_waitcnt lgkmcnt(0)
	v_pk_mul_f32 v[12:13], v[226:227], v[46:47] op_sel_hi:[1,0]
	s_waitcnt lgkmcnt(0)
	v_pk_mul_f32 v[22:23], v[228:229], v[46:47] op_sel_hi:[1,0]
	v_cndmask_b32_e64 v36, v33, v29, s[6:7]
	v_mul_f32_e32 v29, 0xbfb8aa3b, v31
	v_exp_f32_e32 v29, v29
	v_add_f32_e32 v8, 1.0, v8
	v_cndmask_b32_e64 v33, v32, v28, s[6:7]
	v_rcp_f32_e32 v28, v8
	v_add_f32_e32 v8, 1.0, v29
	v_rcp_f32_e32 v29, v8
	v_pk_mul_f32 v[14:15], v[224:225], v[46:47] op_sel_hi:[1,0]
	v_lshlrev_b32_e32 v32, 16, v33
	v_and_b32_e32 v33, 0xffff0000, v33
	v_pk_mul_f32 v[14:15], v[14:15], v[32:33]
	v_pk_mul_f32 v[28:29], v[28:29], v[30:31]
	v_and_b32_e32 v31, 0xffff0000, v36
	v_pk_mul_f32 v[14:15], v[28:29], v[14:15]
	v_lshlrev_b32_e32 v28, 16, v9
	v_and_b32_e32 v29, 0xffff0000, v9
	v_mul_f32_e32 v8, 0xbfb8aa3b, v28
	v_exp_f32_e32 v9, v8
	v_mul_f32_e32 v8, 0xbfb8aa3b, v29
	v_exp_f32_e32 v30, v8
	v_cvt_pk_bf16_f32 v8, v14, v15
	v_add_f32_e32 v9, 1.0, v9
	v_rcp_f32_e32 v14, v9
	v_add_f32_e32 v9, 1.0, v30
	v_rcp_f32_e32 v15, v9
	v_lshlrev_b32_e32 v30, 16, v36
	v_pk_mul_f32 v[12:13], v[12:13], v[30:31]
	v_pk_mul_f32 v[20:21], v[230:231], v[46:47] op_sel_hi:[1,0]
	v_pk_mul_f32 v[14:15], v[14:15], v[28:29]
	v_and_b32_e32 v29, 0xffff0000, v34
	v_pk_mul_f32 v[12:13], v[14:15], v[12:13]
	v_lshlrev_b32_e32 v14, 16, v10
	v_and_b32_e32 v15, 0xffff0000, v10
	v_mul_f32_e32 v9, 0xbfb8aa3b, v14
	v_exp_f32_e32 v10, v9
	v_mul_f32_e32 v9, 0xbfb8aa3b, v15
	v_exp_f32_e32 v28, v9
	v_cvt_pk_bf16_f32 v9, v12, v13
	v_add_f32_e32 v10, 1.0, v10
	v_rcp_f32_e32 v12, v10
	v_add_f32_e32 v10, 1.0, v28
	v_rcp_f32_e32 v13, v10
	v_lshlrev_b32_e32 v28, 16, v34
	v_pk_mul_f32 v[22:23], v[22:23], v[28:29]
	v_pk_mul_f32 v[12:13], v[12:13], v[14:15]
	v_lshlrev_b32_e32 v14, 16, v11
	v_and_b32_e32 v15, 0xffff0000, v11
	v_mul_f32_e32 v10, 0xbfb8aa3b, v14
	v_exp_f32_e32 v11, v10
	v_mul_f32_e32 v10, 0xbfb8aa3b, v15
	v_pk_mul_f32 v[12:13], v[12:13], v[22:23]
	v_exp_f32_e32 v22, v10
	v_add_f32_e32 v11, 1.0, v11
	v_cvt_pk_bf16_f32 v10, v12, v13
	v_rcp_f32_e32 v12, v11
	v_add_f32_e32 v11, 1.0, v22
	v_rcp_f32_e32 v13, v11
	v_lshlrev_b32_e32 v22, 16, v35
	v_and_b32_e32 v23, 0xffff0000, v35
	v_pk_mul_f32 v[20:21], v[20:21], v[22:23]
	v_pk_mul_f32 v[22:23], v[12:13], v[14:15]
	v_pk_mul_f32 v[28:29], v[22:23], v[20:21]
	v_cvt_pk_bf16_f32 v11, v28, v29
	global_store_dwordx4 v[44:45], v[8:11], off offset:32
	v_cndmask_b32_e64 v3, v27, v19, s[6:7]
	v_and_b32_e32 v19, 0xffff0000, v4
	s_waitcnt lgkmcnt(0)
	v_pk_mul_f32 v[10:11], v[232:233], v[46:47] op_sel_hi:[1,0]
	s_waitcnt lgkmcnt(0)
	v_pk_mul_f32 v[12:13], v[238:239], v[46:47] op_sel_hi:[1,0]
	v_cndmask_b32_e64 v22, v26, v18, s[6:7]
	v_lshlrev_b32_e32 v18, 16, v4
	v_mul_f32_e32 v4, 0xbfb8aa3b, v18
	v_cndmask_b32_e64 v23, v25, v17, s[6:7]
	v_exp_f32_e32 v4, v4
	v_mul_f32_e32 v17, 0xbfb8aa3b, v19
	v_exp_f32_e32 v17, v17
	v_pk_mul_f32 v[8:9], v[234:235], v[46:47] op_sel_hi:[1,0]
	v_add_f32_e32 v4, 1.0, v4
	v_pk_mul_f32 v[14:15], v[236:237], v[46:47] op_sel_hi:[1,0]
	v_cndmask_b32_e64 v21, v24, v16, s[6:7]
	v_rcp_f32_e32 v16, v4
	v_add_f32_e32 v4, 1.0, v17
	v_rcp_f32_e32 v17, v4
	v_lshlrev_b32_e32 v20, 16, v21
	v_and_b32_e32 v21, 0xffff0000, v21
	v_pk_mul_f32 v[10:11], v[10:11], v[20:21]
	v_pk_mul_f32 v[16:17], v[16:17], v[18:19]
	v_and_b32_e32 v19, 0xffff0000, v23
	v_pk_mul_f32 v[10:11], v[16:17], v[10:11]
	v_lshlrev_b32_e32 v16, 16, v5
	v_and_b32_e32 v17, 0xffff0000, v5
	v_mul_f32_e32 v4, 0xbfb8aa3b, v16
	v_exp_f32_e32 v5, v4
	v_mul_f32_e32 v4, 0xbfb8aa3b, v17
	v_exp_f32_e32 v18, v4
	v_cvt_pk_bf16_f32 v4, v10, v11
	v_add_f32_e32 v5, 1.0, v5
	v_rcp_f32_e32 v10, v5
	v_add_f32_e32 v5, 1.0, v18
	v_rcp_f32_e32 v11, v5
	v_lshlrev_b32_e32 v18, 16, v23
	v_pk_mul_f32 v[8:9], v[8:9], v[18:19]
	v_pk_mul_f32 v[10:11], v[10:11], v[16:17]
	s_nop 0
	v_pk_mul_f32 v[8:9], v[10:11], v[8:9]
	v_lshlrev_b32_e32 v10, 16, v6
	v_and_b32_e32 v11, 0xffff0000, v6
	v_mul_f32_e32 v5, 0xbfb8aa3b, v10
	v_exp_f32_e32 v6, v5
	v_mul_f32_e32 v5, 0xbfb8aa3b, v11
	v_exp_f32_e32 v16, v5
	v_cvt_pk_bf16_f32 v5, v8, v9
	v_add_f32_e32 v6, 1.0, v6
	v_rcp_f32_e32 v8, v6
	v_add_f32_e32 v6, 1.0, v16
	v_rcp_f32_e32 v9, v6
	v_lshlrev_b32_e32 v16, 16, v22
	v_and_b32_e32 v17, 0xffff0000, v22
	v_pk_mul_f32 v[14:15], v[14:15], v[16:17]
	v_pk_mul_f32 v[8:9], v[8:9], v[10:11]
	v_lshlrev_b32_e32 v10, 16, v7
	v_and_b32_e32 v11, 0xffff0000, v7
	v_mul_f32_e32 v6, 0xbfb8aa3b, v10
	v_exp_f32_e32 v7, v6
	v_mul_f32_e32 v6, 0xbfb8aa3b, v11
	v_pk_mul_f32 v[8:9], v[8:9], v[14:15]
	v_exp_f32_e32 v14, v6
	v_add_f32_e32 v7, 1.0, v7
	v_cvt_pk_bf16_f32 v6, v8, v9
	v_rcp_f32_e32 v8, v7
	v_add_f32_e32 v7, 1.0, v14
	v_rcp_f32_e32 v9, v7
	v_lshlrev_b32_e32 v14, 16, v3
	v_and_b32_e32 v15, 0xffff0000, v3
	v_pk_mul_f32 v[12:13], v[12:13], v[14:15]
	v_pk_mul_f32 v[8:9], v[8:9], v[10:11]
	s_nop 0
	v_pk_mul_f32 v[8:9], v[8:9], v[12:13]
	s_nop 0
	v_cvt_pk_bf16_f32 v7, v8, v9
	global_store_dwordx4 v[44:45], v[4:7], off offset:48

; #define LBAR() do { asm volatile("s_waitcnt lgkmcnt(0)" ::: "memory"); __builtin_amdgcn_s_barrier(); asm volatile("" ::: "memory"); } while (0)
; #define GZLOAD(ZR, chunk) do { const bf16_t* zp_ = proj + (size_t)(b * SEQ + (chunk) * 64 + lane) * NINP + C_GZ + h * 64 + 32 * hc; \
;         _Pragma("unroll") for (int k = 0; k < 4; ++k) ZR[k] = *(const u32x4*)(zp_ + 8 * k); } while (0)
; DI void gdn_scan(const Ctx& c, int bh, const unsigned char* gbase, const float* GL, bf16_t* proj, const float* normw) {
;     ...
;     if (wid >= 6) {
;         const int hc = wid - 6;
;         u32x4 zA[4], zB[4];
;         GZLOAD(zA, 0);
;         for (int n = 0; n < 64; n += 2) {
;             LBAR(); if (n > 0) GHELP(n - 1, zB); GZLOAD(zB, n + 1);
;             LBAR(); GHELP(n, zA); { const int nx = n + 2 < 64 ? n + 2 : 63; GZLOAD(zA, nx); }
.LBB0_2195:
	s_nop 0
	v_add_u32_e32 v4, s33, v64
	v_mov_b64_e32 v[60:61], s[8:9]
	v_mad_i64_i32 v[20:21], s[82:83], v4, s79, v[60:61]
	global_load_dwordx4 v[4:7], v[20:21], off offset:3120
	global_load_dwordx4 v[8:11], v[20:21], off offset:3104
	global_load_dwordx4 v[12:15], v[20:21], off offset:3088
	s_nop 0
	global_load_dwordx4 v[20:23], v[20:21], off offset:3072
	s_waitcnt lgkmcnt(0)
	s_barrier
	v_add_u32_e32 v40, 0x1e200, v135
	ds_read_b128 v[66:69], v40
	ds_read_b128 v[52:55], v40 offset:16
	ds_read_b128 v[44:47], v40 offset:32
	ds_read_b128 v[36:39], v40 offset:48
	ds_read_b128 v[70:73], v40 offset:64
	ds_read_b128 v[56:59], v40 offset:80
	ds_read_b128 v[48:51], v40 offset:96
	ds_read_b128 v[40:43], v40 offset:112
	s_waitcnt lgkmcnt(0)
	v_and_b32_e32 v77, 0xffff0000, v52
	v_and_b32_e32 v76, 0xffff0000, v66
	v_lshlrev_b32_e32 v75, 16, v52
	v_lshlrev_b32_e32 v74, 16, v66
	v_pk_mul_f32 v[76:77], v[76:77], v[76:77]
	v_and_b32_e32 v79, 0xffff0000, v36
	v_pk_fma_f32 v[74:75], v[74:75], v[74:75], v[76:77]
	v_lshlrev_b32_e32 v77, 16, v53
	v_lshlrev_b32_e32 v76, 16, v67
	v_pk_fma_f32 v[74:75], v[76:77], v[76:77], v[74:75]
	v_and_b32_e32 v77, 0xffff0000, v53
	v_and_b32_e32 v76, 0xffff0000, v67
	v_pk_fma_f32 v[74:75], v[76:77], v[76:77], v[74:75]
	v_lshlrev_b32_e32 v77, 16, v54
	v_lshlrev_b32_e32 v76, 16, v68
	v_pk_fma_f32 v[74:75], v[76:77], v[76:77], v[74:75]
	v_and_b32_e32 v77, 0xffff0000, v54
	v_and_b32_e32 v76, 0xffff0000, v68
	v_pk_fma_f32 v[74:75], v[76:77], v[76:77], v[74:75]
	v_lshlrev_b32_e32 v77, 16, v55
	v_lshlrev_b32_e32 v76, 16, v69
	v_pk_fma_f32 v[74:75], v[76:77], v[76:77], v[74:75]
	v_and_b32_e32 v77, 0xffff0000, v55
	v_and_b32_e32 v76, 0xffff0000, v69
	v_and_b32_e32 v78, 0xffff0000, v44
	v_pk_fma_f32 v[74:75], v[76:77], v[76:77], v[74:75]
	v_lshlrev_b32_e32 v77, 16, v36
	v_lshlrev_b32_e32 v76, 16, v44
	v_pk_mul_f32 v[78:79], v[78:79], v[78:79]
	v_and_b32_e32 v81, 0xffff0000, v56
	v_pk_fma_f32 v[76:77], v[76:77], v[76:77], v[78:79]
	v_lshlrev_b32_e32 v79, 16, v37
	v_lshlrev_b32_e32 v78, 16, v45
	v_pk_fma_f32 v[76:77], v[78:79], v[78:79], v[76:77]
	v_and_b32_e32 v79, 0xffff0000, v37
	v_and_b32_e32 v78, 0xffff0000, v45
	v_pk_fma_f32 v[76:77], v[78:79], v[78:79], v[76:77]
	v_lshlrev_b32_e32 v79, 16, v38
	v_lshlrev_b32_e32 v78, 16, v46
	v_pk_fma_f32 v[76:77], v[78:79], v[78:79], v[76:77]
	v_and_b32_e32 v79, 0xffff0000, v38
	v_and_b32_e32 v78, 0xffff0000, v46
	v_pk_fma_f32 v[76:77], v[78:79], v[78:79], v[76:77]
	v_lshlrev_b32_e32 v79, 16, v39
	v_lshlrev_b32_e32 v78, 16, v47
	v_pk_fma_f32 v[76:77], v[78:79], v[78:79], v[76:77]
	v_and_b32_e32 v79, 0xffff0000, v39
	v_and_b32_e32 v78, 0xffff0000, v47
	v_and_b32_e32 v80, 0xffff0000, v70
	v_pk_fma_f32 v[76:77], v[78:79], v[78:79], v[76:77]
	v_lshlrev_b32_e32 v79, 16, v56
	v_lshlrev_b32_e32 v78, 16, v70
	v_pk_mul_f32 v[80:81], v[80:81], v[80:81]
	v_and_b32_e32 v83, 0xffff0000, v40
	v_pk_fma_f32 v[78:79], v[78:79], v[78:79], v[80:81]
	v_lshlrev_b32_e32 v81, 16, v57
	v_lshlrev_b32_e32 v80, 16, v71
	v_pk_fma_f32 v[78:79], v[80:81], v[80:81], v[78:79]
	v_and_b32_e32 v81, 0xffff0000, v57
	v_and_b32_e32 v80, 0xffff0000, v71
	v_pk_fma_f32 v[78:79], v[80:81], v[80:81], v[78:79]
	v_lshlrev_b32_e32 v81, 16, v58
	v_lshlrev_b32_e32 v80, 16, v72
	v_pk_fma_f32 v[78:79], v[80:81], v[80:81], v[78:79]
	v_and_b32_e32 v81, 0xffff0000, v58
	v_and_b32_e32 v80, 0xffff0000, v72
	v_pk_fma_f32 v[78:79], v[80:81], v[80:81], v[78:79]
	v_lshlrev_b32_e32 v81, 16, v59
	v_lshlrev_b32_e32 v80, 16, v73
	v_pk_fma_f32 v[78:79], v[80:81], v[80:81], v[78:79]
	v_and_b32_e32 v81, 0xffff0000, v59
	v_and_b32_e32 v80, 0xffff0000, v73
	v_and_b32_e32 v82, 0xffff0000, v48
	v_pk_fma_f32 v[78:79], v[80:81], v[80:81], v[78:79]
	v_lshlrev_b32_e32 v81, 16, v40
	v_lshlrev_b32_e32 v80, 16, v48
	v_pk_mul_f32 v[82:83], v[82:83], v[82:83]
	v_add_u32_e32 v65, s33, v63
	v_pk_fma_f32 v[80:81], v[80:81], v[80:81], v[82:83]
	v_lshlrev_b32_e32 v83, 16, v41
	v_lshlrev_b32_e32 v82, 16, v49
	v_pk_fma_f32 v[80:81], v[82:83], v[82:83], v[80:81]
	v_and_b32_e32 v83, 0xffff0000, v41
	v_and_b32_e32 v82, 0xffff0000, v49
	v_cndmask_b32_e64 v72, v72, v68, s[6:7]
	s_waitcnt vmcnt(4)
	v_lshlrev_b32_e32 v68, 16, v32
	v_pk_fma_f32 v[80:81], v[82:83], v[82:83], v[80:81]
	v_lshlrev_b32_e32 v83, 16, v42
	v_lshlrev_b32_e32 v82, 16, v50
	v_add_f32_e32 v62, v74, v75
	v_mad_i64_i32 v[60:61], s[82:83], v65, s79, v[60:61]
	v_cndmask_b32_e64 v65, v73, v69, s[6:7]
	v_and_b32_e32 v69, 0xffff0000, v32
	v_mul_f32_e32 v32, 0xbfb8aa3b, v68
	v_pk_fma_f32 v[80:81], v[82:83], v[82:83], v[80:81]
	v_and_b32_e32 v83, 0xffff0000, v42
	v_and_b32_e32 v82, 0xffff0000, v50
	v_add_f32_e32 v62, v62, v76
	v_cndmask_b32_e64 v73, v71, v67, s[6:7]
	v_exp_f32_e32 v32, v32
	v_mul_f32_e32 v67, 0xbfb8aa3b, v69
	v_pk_fma_f32 v[80:81], v[82:83], v[82:83], v[80:81]
	v_lshlrev_b32_e32 v83, 16, v43
	v_lshlrev_b32_e32 v82, 16, v51
	v_add_f32_e32 v62, v62, v77
	v_exp_f32_e32 v67, v67
	v_pk_fma_f32 v[80:81], v[82:83], v[82:83], v[80:81]
	v_and_b32_e32 v83, 0xffff0000, v43
	v_and_b32_e32 v82, 0xffff0000, v51
	v_add_f32_e32 v62, v62, v78
	v_pk_fma_f32 v[80:81], v[82:83], v[82:83], v[80:81]
	v_add_f32_e32 v62, v62, v79
	v_add_f32_e32 v62, v62, v80
	v_add_f32_e32 v32, 1.0, v32
	v_add_f32_e32 v62, v62, v81
	v_mov_b32_e32 v90, s75
	v_cndmask_b32_e64 v71, v70, v66, s[6:7]
	v_rcp_f32_e32 v66, v32
	v_add_f32_e32 v32, 1.0, v67
	v_fmamk_f32 v62, v62, 0x3c800000, v134
	v_rcp_f32_e32 v67, v32
	v_rsq_f32_e32 v62, v62
	v_lshlrev_b32_e32 v70, 16, v71
	v_and_b32_e32 v71, 0xffff0000, v71
	v_pk_mul_f32 v[66:67], v[66:67], v[68:69]
	v_lshlrev_b32_e32 v68, 16, v33
	s_waitcnt lgkmcnt(0)
	v_pk_mul_f32 v[74:75], v[208:209], v[62:63] op_sel_hi:[1,0]
	v_and_b32_e32 v69, 0xffff0000, v33
	v_mul_f32_e32 v32, 0xbfb8aa3b, v68
	v_pk_mul_f32 v[70:71], v[74:75], v[70:71]
	v_exp_f32_e32 v33, v32
	v_mul_f32_e32 v32, 0xbfb8aa3b, v69
	v_pk_mul_f32 v[66:67], v[66:67], v[70:71]
	v_exp_f32_e32 v70, v32
	v_add_f32_e32 v33, 1.0, v33
	v_cvt_pk_bf16_f32 v32, v66, v67
	v_rcp_f32_e32 v66, v33
	v_add_f32_e32 v33, 1.0, v70
	v_rcp_f32_e32 v67, v33
	v_pk_mul_f32 v[76:77], v[210:211], v[62:63] op_sel_hi:[1,0]
	v_lshlrev_b32_e32 v70, 16, v73
	v_and_b32_e32 v71, 0xffff0000, v73
	v_pk_mul_f32 v[66:67], v[66:67], v[68:69]
	v_lshlrev_b32_e32 v68, 16, v34
	v_and_b32_e32 v69, 0xffff0000, v34
	v_mul_f32_e32 v33, 0xbfb8aa3b, v68
	v_pk_mul_f32 v[70:71], v[76:77], v[70:71]
	v_exp_f32_e32 v34, v33
	v_mul_f32_e32 v33, 0xbfb8aa3b, v69
	v_pk_mul_f32 v[66:67], v[66:67], v[70:71]
	v_exp_f32_e32 v70, v33
	v_add_f32_e32 v34, 1.0, v34
	v_cvt_pk_bf16_f32 v33, v66, v67
	v_rcp_f32_e32 v66, v34
	v_add_f32_e32 v34, 1.0, v70
	v_rcp_f32_e32 v67, v34
	v_lshlrev_b32_e32 v70, 16, v72
	v_and_b32_e32 v71, 0xffff0000, v72
	v_pk_mul_f32 v[66:67], v[66:67], v[68:69]
	v_lshlrev_b32_e32 v68, 16, v35
	s_waitcnt lgkmcnt(0)
	v_pk_mul_f32 v[78:79], v[212:213], v[62:63] op_sel_hi:[1,0]
	v_and_b32_e32 v69, 0xffff0000, v35
	v_mul_f32_e32 v34, 0xbfb8aa3b, v68
	v_pk_mul_f32 v[70:71], v[78:79], v[70:71]
	v_exp_f32_e32 v35, v34
	v_mul_f32_e32 v34, 0xbfb8aa3b, v69
	v_pk_mul_f32 v[66:67], v[66:67], v[70:71]
	v_exp_f32_e32 v70, v34
	v_cndmask_b32_e64 v58, v58, v54, s[6:7]
	v_lshlrev_b32_e32 v54, 16, v28
	v_add_f32_e32 v35, 1.0, v35
	v_cndmask_b32_e64 v59, v59, v55, s[6:7]
	v_and_b32_e32 v55, 0xffff0000, v28
	v_mul_f32_e32 v28, 0xbfb8aa3b, v54
	v_cvt_pk_bf16_f32 v34, v66, v67
	v_rcp_f32_e32 v66, v35
	v_add_f32_e32 v35, 1.0, v70
	v_lshlrev_b32_e32 v70, 16, v65
	v_and_b32_e32 v71, 0xffff0000, v65
	v_cndmask_b32_e64 v65, v57, v53, s[6:7]
	v_exp_f32_e32 v28, v28
	v_mul_f32_e32 v53, 0xbfb8aa3b, v55
	v_exp_f32_e32 v53, v53
	v_rcp_f32_e32 v67, v35
	v_add_f32_e32 v28, 1.0, v28
	v_pk_mul_f32 v[80:81], v[214:215], v[62:63] op_sel_hi:[1,0]
	v_cndmask_b32_e64 v57, v56, v52, s[6:7]
	v_rcp_f32_e32 v52, v28
	v_add_f32_e32 v28, 1.0, v53
	v_pk_mul_f32 v[70:71], v[80:81], v[70:71]
	v_pk_mul_f32 v[66:67], v[66:67], v[68:69]
	v_rcp_f32_e32 v53, v28
	v_pk_mul_f32 v[66:67], v[66:67], v[70:71]
	v_lshlrev_b32_e32 v56, 16, v57
	v_cvt_pk_bf16_f32 v35, v66, v67
	global_store_dwordx4 v[60:61], v[32:35], off
	v_and_b32_e32 v57, 0xffff0000, v57
	v_pk_mul_f32 v[52:53], v[52:53], v[54:55]
	s_waitcnt lgkmcnt(0)
	v_pk_mul_f32 v[34:35], v[216:217], v[62:63] op_sel_hi:[1,0]
	v_pk_mul_f32 v[32:33], v[218:219], v[62:63] op_sel_hi:[1,0]
	v_pk_mul_f32 v[34:35], v[34:35], v[56:57]
	v_and_b32_e32 v55, 0xffff0000, v65
	v_pk_mul_f32 v[34:35], v[52:53], v[34:35]
	v_lshlrev_b32_e32 v52, 16, v29
	v_and_b32_e32 v53, 0xffff0000, v29
	v_mul_f32_e32 v28, 0xbfb8aa3b, v52
	v_exp_f32_e32 v29, v28
	v_mul_f32_e32 v28, 0xbfb8aa3b, v53
	v_exp_f32_e32 v54, v28
	v_cvt_pk_bf16_f32 v28, v34, v35
	v_add_f32_e32 v29, 1.0, v29
	v_rcp_f32_e32 v34, v29
	v_add_f32_e32 v29, 1.0, v54
	v_rcp_f32_e32 v35, v29
	v_lshlrev_b32_e32 v54, 16, v65
	v_pk_mul_f32 v[32:33], v[32:33], v[54:55]
	s_waitcnt lgkmcnt(0)
	v_pk_mul_f32 v[68:69], v[220:221], v[62:63] op_sel_hi:[1,0]
	v_pk_mul_f32 v[34:35], v[34:35], v[52:53]
	v_and_b32_e32 v53, 0xffff0000, v58
	v_pk_mul_f32 v[32:33], v[34:35], v[32:33]
	v_lshlrev_b32_e32 v34, 16, v30
	v_and_b32_e32 v35, 0xffff0000, v30
	v_mul_f32_e32 v29, 0xbfb8aa3b, v34
	v_exp_f32_e32 v30, v29
	v_mul_f32_e32 v29, 0xbfb8aa3b, v35
	v_exp_f32_e32 v52, v29
	v_cvt_pk_bf16_f32 v29, v32, v33
	v_add_f32_e32 v30, 1.0, v30
	v_rcp_f32_e32 v32, v30
	v_add_f32_e32 v30, 1.0, v52
	v_rcp_f32_e32 v33, v30
	v_lshlrev_b32_e32 v52, 16, v58
	v_pk_mul_f32 v[52:53], v[68:69], v[52:53]
	v_pk_mul_f32 v[66:67], v[222:223], v[62:63] op_sel_hi:[1,0]
	v_pk_mul_f32 v[32:33], v[32:33], v[34:35]
	v_lshlrev_b32_e32 v34, 16, v31
	v_and_b32_e32 v35, 0xffff0000, v31
	v_mul_f32_e32 v30, 0xbfb8aa3b, v34
	v_exp_f32_e32 v31, v30
	v_mul_f32_e32 v30, 0xbfb8aa3b, v35
	v_pk_mul_f32 v[32:33], v[32:33], v[52:53]
	v_exp_f32_e32 v52, v30
	v_add_f32_e32 v31, 1.0, v31
	v_cvt_pk_bf16_f32 v30, v32, v33
	v_rcp_f32_e32 v32, v31
	v_add_f32_e32 v31, 1.0, v52
	v_rcp_f32_e32 v33, v31
	v_lshlrev_b32_e32 v52, 16, v59
	v_and_b32_e32 v53, 0xffff0000, v59
	v_pk_mul_f32 v[52:53], v[66:67], v[52:53]
	v_pk_mul_f32 v[54:55], v[32:33], v[34:35]
	v_pk_mul_f32 v[56:57], v[54:55], v[52:53]
	v_cndmask_b32_e64 v50, v50, v46, s[6:7]
	v_lshlrev_b32_e32 v46, 16, v24
	v_cvt_pk_bf16_f32 v31, v56, v57
	v_cndmask_b32_e64 v51, v51, v47, s[6:7]
	v_and_b32_e32 v47, 0xffff0000, v24
	v_mul_f32_e32 v24, 0xbfb8aa3b, v46
	global_store_dwordx4 v[60:61], v[28:31], off offset:16
	v_exp_f32_e32 v24, v24
	v_cndmask_b32_e64 v41, v41, v37, s[6:7]
	s_waitcnt lgkmcnt(0)
	v_pk_mul_f32 v[28:29], v[226:227], v[62:63] op_sel_hi:[1,0]
	s_waitcnt lgkmcnt(0)
; #define LBAR() do { asm volatile("s_waitcnt lgkmcnt(0)" ::: "memory"); __builtin_amdgcn_s_barrier(); asm volatile("" ::: "memory"); } while (0)
; #define GZLOAD(ZR, chunk) do { const bf16_t* zp_ = proj + (size_t)(b * SEQ + (chunk) * 64 + lane) * NINP + C_GZ + h * 64 + 32 * hc; \
;         _Pragma("unroll") for (int k = 0; k < 4; ++k) ZR[k] = *(const u32x4*)(zp_ + 8 * k); } while (0)
; DI void gdn_scan(const Ctx& c, int bh, const unsigned char* gbase, const float* GL, bf16_t* proj, const float* normw) {
;     ...
;         for (int n = 0; n < 64; n += 2) {
;             LBAR(); if (n > 0) GHELP(n - 1, zB); GZLOAD(zB, n + 1);
;             LBAR(); GHELP(n, zA); { const int nx = n + 2 < 64 ? n + 2 : 63; GZLOAD(zA, nx); }
	v_pk_mul_f32 v[34:35], v[228:229], v[62:63] op_sel_hi:[1,0]
	v_cndmask_b32_e64 v52, v49, v45, s[6:7]
	v_mul_f32_e32 v45, 0xbfb8aa3b, v47
	v_exp_f32_e32 v45, v45
	v_add_f32_e32 v24, 1.0, v24
	v_cndmask_b32_e64 v49, v48, v44, s[6:7]
	v_rcp_f32_e32 v44, v24
	v_add_f32_e32 v24, 1.0, v45
	v_rcp_f32_e32 v45, v24
	v_pk_mul_f32 v[30:31], v[224:225], v[62:63] op_sel_hi:[1,0]
	v_lshlrev_b32_e32 v48, 16, v49
	v_and_b32_e32 v49, 0xffff0000, v49
	v_pk_mul_f32 v[30:31], v[30:31], v[48:49]
	v_pk_mul_f32 v[44:45], v[44:45], v[46:47]
	v_and_b32_e32 v47, 0xffff0000, v52
	v_pk_mul_f32 v[30:31], v[44:45], v[30:31]
	v_lshlrev_b32_e32 v44, 16, v25
	v_and_b32_e32 v45, 0xffff0000, v25
	v_mul_f32_e32 v24, 0xbfb8aa3b, v44
	v_exp_f32_e32 v25, v24
	v_mul_f32_e32 v24, 0xbfb8aa3b, v45
	v_exp_f32_e32 v46, v24
	v_cvt_pk_bf16_f32 v24, v30, v31
	v_add_f32_e32 v25, 1.0, v25
	v_rcp_f32_e32 v30, v25
	v_add_f32_e32 v25, 1.0, v46
	v_rcp_f32_e32 v31, v25
	v_lshlrev_b32_e32 v46, 16, v52
	v_pk_mul_f32 v[28:29], v[28:29], v[46:47]
	v_pk_mul_f32 v[32:33], v[230:231], v[62:63] op_sel_hi:[1,0]
	v_pk_mul_f32 v[30:31], v[30:31], v[44:45]
	v_and_b32_e32 v45, 0xffff0000, v50
	v_pk_mul_f32 v[28:29], v[30:31], v[28:29]
	v_lshlrev_b32_e32 v30, 16, v26
	v_and_b32_e32 v31, 0xffff0000, v26
	v_mul_f32_e32 v25, 0xbfb8aa3b, v30
	v_exp_f32_e32 v26, v25
	v_mul_f32_e32 v25, 0xbfb8aa3b, v31
	v_exp_f32_e32 v44, v25
	v_cvt_pk_bf16_f32 v25, v28, v29
	v_add_f32_e32 v26, 1.0, v26
	v_rcp_f32_e32 v28, v26
	v_add_f32_e32 v26, 1.0, v44
	v_rcp_f32_e32 v29, v26
	v_lshlrev_b32_e32 v44, 16, v50
	v_pk_mul_f32 v[34:35], v[34:35], v[44:45]
	v_cndmask_b32_e64 v37, v40, v36, s[6:7]
	v_pk_mul_f32 v[28:29], v[28:29], v[30:31]
	v_lshlrev_b32_e32 v30, 16, v27
	v_and_b32_e32 v31, 0xffff0000, v27
	v_mul_f32_e32 v26, 0xbfb8aa3b, v30
	v_exp_f32_e32 v27, v26
	v_mul_f32_e32 v26, 0xbfb8aa3b, v31
	v_pk_mul_f32 v[28:29], v[28:29], v[34:35]
	v_exp_f32_e32 v34, v26
	v_add_f32_e32 v27, 1.0, v27
	v_cvt_pk_bf16_f32 v26, v28, v29
	v_rcp_f32_e32 v28, v27
	v_add_f32_e32 v27, 1.0, v34
	v_rcp_f32_e32 v29, v27
	v_lshlrev_b32_e32 v34, 16, v51
	v_and_b32_e32 v35, 0xffff0000, v51
	v_pk_mul_f32 v[32:33], v[32:33], v[34:35]
	v_pk_mul_f32 v[34:35], v[28:29], v[30:31]
	v_pk_mul_f32 v[44:45], v[34:35], v[32:33]
	v_cvt_pk_bf16_f32 v27, v44, v45
	global_store_dwordx4 v[60:61], v[24:27], off offset:32
	v_lshlrev_b32_e32 v36, 16, v37
	v_and_b32_e32 v37, 0xffff0000, v37
	s_waitcnt lgkmcnt(0)
	v_pk_mul_f32 v[24:25], v[234:235], v[62:63] op_sel_hi:[1,0]
	s_waitcnt lgkmcnt(0)
	v_pk_mul_f32 v[30:31], v[236:237], v[62:63] op_sel_hi:[1,0]
	v_lshlrev_b32_e32 v32, 16, v16
	v_and_b32_e32 v33, 0xffff0000, v16
	v_mul_f32_e32 v16, 0xbfb8aa3b, v32
	v_pk_mul_f32 v[26:27], v[232:233], v[62:63] op_sel_hi:[1,0]
	v_pk_mul_f32 v[28:29], v[238:239], v[62:63] op_sel_hi:[1,0]
	v_exp_f32_e32 v16, v16
	v_mul_f32_e32 v34, 0xbfb8aa3b, v33
	v_exp_f32_e32 v35, v34
	v_pk_mul_f32 v[26:27], v[26:27], v[36:37]
	v_add_f32_e32 v16, 1.0, v16
	v_rcp_f32_e32 v34, v16
	v_add_f32_e32 v16, 1.0, v35
	v_rcp_f32_e32 v35, v16
	v_cndmask_b32_e64 v38, v42, v38, s[6:7]
	v_cndmask_b32_e64 v39, v43, v39, s[6:7]
	s_add_i32 s33, s66, 2
	v_pk_mul_f32 v[32:33], v[34:35], v[32:33]
	v_and_b32_e32 v35, 0xffff0000, v41
	v_pk_mul_f32 v[26:27], v[32:33], v[26:27]
	v_lshlrev_b32_e32 v32, 16, v17
	v_and_b32_e32 v33, 0xffff0000, v17
	v_mul_f32_e32 v16, 0xbfb8aa3b, v32
	v_exp_f32_e32 v17, v16
	v_mul_f32_e32 v16, 0xbfb8aa3b, v33
	v_exp_f32_e32 v34, v16
	v_cvt_pk_bf16_f32 v16, v26, v27
	v_add_f32_e32 v17, 1.0, v17
	v_rcp_f32_e32 v26, v17
	v_add_f32_e32 v17, 1.0, v34
	v_rcp_f32_e32 v27, v17
	v_lshlrev_b32_e32 v34, 16, v41
	v_pk_mul_f32 v[24:25], v[24:25], v[34:35]
	s_addk_i32 s65, 0x80
	v_pk_mul_f32 v[26:27], v[26:27], v[32:33]
	v_and_b32_e32 v33, 0xffff0000, v38
	v_pk_mul_f32 v[24:25], v[26:27], v[24:25]
	v_lshlrev_b32_e32 v26, 16, v18
	v_and_b32_e32 v27, 0xffff0000, v18
	v_mul_f32_e32 v17, 0xbfb8aa3b, v26
	v_exp_f32_e32 v18, v17
	v_mul_f32_e32 v17, 0xbfb8aa3b, v27
	v_exp_f32_e32 v32, v17
	v_cvt_pk_bf16_f32 v17, v24, v25
	v_add_f32_e32 v18, 1.0, v18
	v_rcp_f32_e32 v24, v18
	v_add_f32_e32 v18, 1.0, v32
	v_rcp_f32_e32 v25, v18
	v_lshlrev_b32_e32 v32, 16, v38
	v_pk_mul_f32 v[30:31], v[30:31], v[32:33]
	s_cmp_lt_u32 s66, 62
	v_pk_mul_f32 v[24:25], v[24:25], v[26:27]
	v_lshlrev_b32_e32 v26, 16, v19
	v_and_b32_e32 v27, 0xffff0000, v19
	v_mul_f32_e32 v18, 0xbfb8aa3b, v26
	v_exp_f32_e32 v19, v18
	v_mul_f32_e32 v18, 0xbfb8aa3b, v27
	v_pk_mul_f32 v[24:25], v[24:25], v[30:31]
	v_exp_f32_e32 v30, v18
	v_add_f32_e32 v19, 1.0, v19
	v_cvt_pk_bf16_f32 v18, v24, v25
	v_rcp_f32_e32 v24, v19
	v_add_f32_e32 v19, 1.0, v30
	v_rcp_f32_e32 v25, v19
	v_lshlrev_b32_e32 v30, 16, v39
	v_and_b32_e32 v31, 0xffff0000, v39
	v_pk_mul_f32 v[28:29], v[28:29], v[30:31]
	v_pk_mul_f32 v[24:25], v[24:25], v[26:27]
	s_cselect_b32 s67, s65, 0xfc0
	v_pk_mul_f32 v[24:25], v[24:25], v[28:29]
	s_cmp_gt_u32 s66, 61
	v_cvt_pk_bf16_f32 v19, v24, v25
	global_store_dwordx4 v[60:61], v[16:19], off offset:48
	s_mov_b32 s66, s33
	s_nop 0
	v_add_u32_e32 v16, s67, v63
	s_cbranch_scc1 .LBB0_2172
; #define LBAR() do { asm volatile("s_waitcnt lgkmcnt(0)" ::: "memory"); __builtin_amdgcn_s_barrier(); asm volatile("" ::: "memory"); } while (0)
; #define GZLOAD(ZR, chunk) do { const bf16_t* zp_ = proj + (size_t)(b * SEQ + (chunk) * 64 + lane) * NINP + C_GZ + h * 64 + 32 * hc; \
;         _Pragma("unroll") for (int k = 0; k < 4; ++k) ZR[k] = *(const u32x4*)(zp_ + 8 * k); } while (0)
; DI void gdn_scan(const Ctx& c, int bh, const unsigned char* gbase, const float* GL, bf16_t* proj, const float* normw) {
;     ...
;         for (int n = 0; n < 64; n += 2) {
;             LBAR(); if (n > 0) GHELP(n - 1, zB); GZLOAD(zB, n + 1);
;             LBAR(); GHELP(n, zA); { const int nx = n + 2 < 64 ? n + 2 : 63; GZLOAD(zA, nx); }
.LBB0_2196:
	v_mov_b64_e32 v[18:19], s[8:9]
	v_mad_i64_i32 v[32:33], s[82:83], v16, s79, v[18:19]
	global_load_dwordx4 v[16:19], v[32:33], off offset:3120
	global_load_dwordx4 v[24:27], v[32:33], off offset:3104
	global_load_dwordx4 v[28:31], v[32:33], off offset:3088
	s_nop 0
	global_load_dwordx4 v[32:35], v[32:33], off offset:3072
	s_waitcnt lgkmcnt(0)
	s_barrier
	s_cmp_eq_u32 s65, 0
	s_mov_b32 s33, 0
	s_cbranch_scc1 .Lnwl_init_1
	v_add_u32_e32 v40, 0x20600, v135
	ds_read_b128 v[66:69], v40
	ds_read_b128 v[52:55], v40 offset:16
	ds_read_b128 v[44:47], v40 offset:32
	ds_read_b128 v[36:39], v40 offset:48
	ds_read_b128 v[70:73], v40 offset:64
	ds_read_b128 v[56:59], v40 offset:80
	ds_read_b128 v[48:51], v40 offset:96
	ds_read_b128 v[40:43], v40 offset:112
	s_waitcnt lgkmcnt(0)
	s_waitcnt vmcnt(8)
	v_and_b32_e32 v75, 0xffff0000, v52
	v_and_b32_e32 v74, 0xffff0000, v66
	v_lshlrev_b32_e32 v61, 16, v52
	v_lshlrev_b32_e32 v60, 16, v66
	v_pk_mul_f32 v[74:75], v[74:75], v[74:75]
	v_and_b32_e32 v77, 0xffff0000, v36
	v_pk_fma_f32 v[60:61], v[60:61], v[60:61], v[74:75]
	v_lshlrev_b32_e32 v75, 16, v53
	v_lshlrev_b32_e32 v74, 16, v67
	v_pk_fma_f32 v[60:61], v[74:75], v[74:75], v[60:61]
	v_and_b32_e32 v75, 0xffff0000, v53
	v_and_b32_e32 v74, 0xffff0000, v67
	v_pk_fma_f32 v[60:61], v[74:75], v[74:75], v[60:61]
	v_lshlrev_b32_e32 v75, 16, v54
	v_lshlrev_b32_e32 v74, 16, v68
	v_pk_fma_f32 v[60:61], v[74:75], v[74:75], v[60:61]
	v_and_b32_e32 v75, 0xffff0000, v54
	v_and_b32_e32 v74, 0xffff0000, v68
	v_pk_fma_f32 v[60:61], v[74:75], v[74:75], v[60:61]
	v_lshlrev_b32_e32 v75, 16, v55
	v_lshlrev_b32_e32 v74, 16, v69
	v_pk_fma_f32 v[60:61], v[74:75], v[74:75], v[60:61]
	v_and_b32_e32 v75, 0xffff0000, v55
	v_and_b32_e32 v74, 0xffff0000, v69
	v_and_b32_e32 v76, 0xffff0000, v44
	v_pk_fma_f32 v[60:61], v[74:75], v[74:75], v[60:61]
	v_lshlrev_b32_e32 v75, 16, v36
	v_lshlrev_b32_e32 v74, 16, v44
	v_pk_mul_f32 v[76:77], v[76:77], v[76:77]
	v_and_b32_e32 v79, 0xffff0000, v56
	v_pk_fma_f32 v[74:75], v[74:75], v[74:75], v[76:77]
	v_lshlrev_b32_e32 v77, 16, v37
	v_lshlrev_b32_e32 v76, 16, v45
	v_pk_fma_f32 v[74:75], v[76:77], v[76:77], v[74:75]
	v_and_b32_e32 v77, 0xffff0000, v37
	v_and_b32_e32 v76, 0xffff0000, v45
	v_pk_fma_f32 v[74:75], v[76:77], v[76:77], v[74:75]
	v_lshlrev_b32_e32 v77, 16, v38
	v_lshlrev_b32_e32 v76, 16, v46
	v_pk_fma_f32 v[74:75], v[76:77], v[76:77], v[74:75]
	v_and_b32_e32 v77, 0xffff0000, v38
	v_and_b32_e32 v76, 0xffff0000, v46
	v_pk_fma_f32 v[74:75], v[76:77], v[76:77], v[74:75]
	v_lshlrev_b32_e32 v77, 16, v39
	v_lshlrev_b32_e32 v76, 16, v47
	v_pk_fma_f32 v[74:75], v[76:77], v[76:77], v[74:75]
	v_and_b32_e32 v77, 0xffff0000, v39
	v_and_b32_e32 v76, 0xffff0000, v47
	v_and_b32_e32 v78, 0xffff0000, v70
	v_pk_fma_f32 v[74:75], v[76:77], v[76:77], v[74:75]
	v_lshlrev_b32_e32 v77, 16, v56
	v_lshlrev_b32_e32 v76, 16, v70
	v_pk_mul_f32 v[78:79], v[78:79], v[78:79]
	v_and_b32_e32 v81, 0xffff0000, v40
	v_pk_fma_f32 v[76:77], v[76:77], v[76:77], v[78:79]
	v_lshlrev_b32_e32 v79, 16, v57
	v_lshlrev_b32_e32 v78, 16, v71
	v_pk_fma_f32 v[76:77], v[78:79], v[78:79], v[76:77]
	v_and_b32_e32 v79, 0xffff0000, v57
	v_and_b32_e32 v78, 0xffff0000, v71
	v_pk_fma_f32 v[76:77], v[78:79], v[78:79], v[76:77]
	v_lshlrev_b32_e32 v79, 16, v58
	v_lshlrev_b32_e32 v78, 16, v72
	v_pk_fma_f32 v[76:77], v[78:79], v[78:79], v[76:77]
	v_and_b32_e32 v79, 0xffff0000, v58
	v_and_b32_e32 v78, 0xffff0000, v72
	v_pk_fma_f32 v[76:77], v[78:79], v[78:79], v[76:77]
	v_lshlrev_b32_e32 v79, 16, v59
	v_lshlrev_b32_e32 v78, 16, v73
	v_pk_fma_f32 v[76:77], v[78:79], v[78:79], v[76:77]
	v_and_b32_e32 v79, 0xffff0000, v59
	v_and_b32_e32 v78, 0xffff0000, v73
	v_and_b32_e32 v80, 0xffff0000, v48
	v_pk_fma_f32 v[76:77], v[78:79], v[78:79], v[76:77]
	v_lshlrev_b32_e32 v79, 16, v40
	v_lshlrev_b32_e32 v78, 16, v48
	v_pk_mul_f32 v[80:81], v[80:81], v[80:81]
	v_add_f32_e32 v60, v60, v61
	v_pk_fma_f32 v[78:79], v[78:79], v[78:79], v[80:81]
	v_lshlrev_b32_e32 v81, 16, v41
	v_lshlrev_b32_e32 v80, 16, v49
	v_pk_fma_f32 v[78:79], v[80:81], v[80:81], v[78:79]
	v_and_b32_e32 v81, 0xffff0000, v41
	v_and_b32_e32 v80, 0xffff0000, v49
	v_pk_fma_f32 v[78:79], v[80:81], v[80:81], v[78:79]
	v_lshlrev_b32_e32 v81, 16, v42
	v_lshlrev_b32_e32 v80, 16, v50
	v_pk_fma_f32 v[78:79], v[80:81], v[80:81], v[78:79]
	v_and_b32_e32 v81, 0xffff0000, v42
	v_and_b32_e32 v80, 0xffff0000, v50
	v_add_f32_e32 v60, v60, v74
	v_pk_fma_f32 v[78:79], v[80:81], v[80:81], v[78:79]
	v_lshlrev_b32_e32 v81, 16, v43
	v_lshlrev_b32_e32 v80, 16, v51
	v_add_f32_e32 v60, v60, v75
	v_pk_fma_f32 v[78:79], v[80:81], v[80:81], v[78:79]
	v_and_b32_e32 v81, 0xffff0000, v43
	v_and_b32_e32 v80, 0xffff0000, v51
	v_add_f32_e32 v60, v60, v76
	v_pk_fma_f32 v[78:79], v[80:81], v[80:81], v[78:79]
	v_add_f32_e32 v60, v60, v77
	v_add_f32_e32 v60, v60, v78
	v_add_f32_e32 v60, v60, v79
	v_fmamk_f32 v60, v60, 0x3c800000, v134
	v_rsq_f32_e32 v62, v60
	v_add_u32_e32 v65, s65, v3
	v_mov_b64_e32 v[60:61], s[8:9]
	v_cndmask_b32_e64 v72, v72, v68, s[6:7]
	v_lshlrev_b32_e32 v68, 16, v20
	v_mad_i64_i32 v[60:61], s[82:83], v65, s79, v[60:61]
	v_cndmask_b32_e64 v65, v73, v69, s[6:7]
	v_and_b32_e32 v69, 0xffff0000, v20
	v_mul_f32_e32 v20, 0xbfb8aa3b, v68
	v_cndmask_b32_e64 v73, v71, v67, s[6:7]
	v_exp_f32_e32 v20, v20
	v_mul_f32_e32 v67, 0xbfb8aa3b, v69
	v_exp_f32_e32 v67, v67
	v_mov_b32_e32 v90, s75
	v_add_f32_e32 v20, 1.0, v20
	v_cndmask_b32_e64 v71, v70, v66, s[6:7]
	v_rcp_f32_e32 v66, v20
	v_add_f32_e32 v20, 1.0, v67
	v_rcp_f32_e32 v67, v20
	v_lshlrev_b32_e32 v70, 16, v71
	v_and_b32_e32 v71, 0xffff0000, v71
	v_pk_mul_f32 v[66:67], v[66:67], v[68:69]
	v_lshlrev_b32_e32 v68, 16, v21
	s_waitcnt lgkmcnt(0)
	v_pk_mul_f32 v[74:75], v[208:209], v[62:63] op_sel_hi:[1,0]
	v_and_b32_e32 v69, 0xffff0000, v21
	v_mul_f32_e32 v20, 0xbfb8aa3b, v68
	v_pk_mul_f32 v[70:71], v[74:75], v[70:71]
	v_exp_f32_e32 v21, v20
	v_mul_f32_e32 v20, 0xbfb8aa3b, v69
	v_pk_mul_f32 v[66:67], v[66:67], v[70:71]
	v_exp_f32_e32 v70, v20
	v_add_f32_e32 v21, 1.0, v21
	v_cvt_pk_bf16_f32 v20, v66, v67
	v_rcp_f32_e32 v66, v21
	v_add_f32_e32 v21, 1.0, v70
	v_rcp_f32_e32 v67, v21
	v_pk_mul_f32 v[76:77], v[210:211], v[62:63] op_sel_hi:[1,0]
	v_lshlrev_b32_e32 v70, 16, v73
	v_and_b32_e32 v71, 0xffff0000, v73
	v_pk_mul_f32 v[66:67], v[66:67], v[68:69]
	v_lshlrev_b32_e32 v68, 16, v22
	v_and_b32_e32 v69, 0xffff0000, v22
	v_mul_f32_e32 v21, 0xbfb8aa3b, v68
	v_pk_mul_f32 v[70:71], v[76:77], v[70:71]
	v_exp_f32_e32 v22, v21
	v_mul_f32_e32 v21, 0xbfb8aa3b, v69
	v_pk_mul_f32 v[66:67], v[66:67], v[70:71]
	v_exp_f32_e32 v70, v21
	v_add_f32_e32 v22, 1.0, v22
	v_cvt_pk_bf16_f32 v21, v66, v67
	v_rcp_f32_e32 v66, v22
	v_add_f32_e32 v22, 1.0, v70
	v_rcp_f32_e32 v67, v22
	v_pk_mul_f32 v[78:79], v[212:213], v[62:63] op_sel_hi:[1,0]
	v_lshlrev_b32_e32 v70, 16, v72
	v_and_b32_e32 v71, 0xffff0000, v72
	v_pk_mul_f32 v[66:67], v[66:67], v[68:69]
	v_lshlrev_b32_e32 v68, 16, v23
	v_and_b32_e32 v69, 0xffff0000, v23
	v_mul_f32_e32 v22, 0xbfb8aa3b, v68
	v_pk_mul_f32 v[70:71], v[78:79], v[70:71]
	v_exp_f32_e32 v23, v22
	v_mul_f32_e32 v22, 0xbfb8aa3b, v69
	v_pk_mul_f32 v[66:67], v[66:67], v[70:71]
	v_exp_f32_e32 v70, v22
	v_cndmask_b32_e64 v58, v58, v54, s[6:7]
	v_lshlrev_b32_e32 v54, 16, v12
	v_add_f32_e32 v23, 1.0, v23
	v_cndmask_b32_e64 v59, v59, v55, s[6:7]
	v_and_b32_e32 v55, 0xffff0000, v12
	v_mul_f32_e32 v12, 0xbfb8aa3b, v54
	v_cvt_pk_bf16_f32 v22, v66, v67
	v_rcp_f32_e32 v66, v23
	v_add_f32_e32 v23, 1.0, v70
	v_lshlrev_b32_e32 v70, 16, v65
	v_and_b32_e32 v71, 0xffff0000, v65
	v_cndmask_b32_e64 v65, v57, v53, s[6:7]
	v_exp_f32_e32 v12, v12
	v_mul_f32_e32 v53, 0xbfb8aa3b, v55
	v_exp_f32_e32 v53, v53
	v_rcp_f32_e32 v67, v23
	v_add_f32_e32 v12, 1.0, v12
	v_pk_mul_f32 v[80:81], v[214:215], v[62:63] op_sel_hi:[1,0]
	v_cndmask_b32_e64 v57, v56, v52, s[6:7]
	v_rcp_f32_e32 v52, v12
	v_add_f32_e32 v12, 1.0, v53
	v_pk_mul_f32 v[70:71], v[80:81], v[70:71]
	v_pk_mul_f32 v[66:67], v[66:67], v[68:69]
	v_rcp_f32_e32 v53, v12
	v_pk_mul_f32 v[66:67], v[66:67], v[70:71]
	v_lshlrev_b32_e32 v56, 16, v57
	v_cvt_pk_bf16_f32 v23, v66, v67
	global_store_dwordx4 v[60:61], v[20:23], off
	v_and_b32_e32 v57, 0xffff0000, v57
	v_pk_mul_f32 v[52:53], v[52:53], v[54:55]
	v_pk_mul_f32 v[22:23], v[216:217], v[62:63] op_sel_hi:[1,0]
	v_pk_mul_f32 v[20:21], v[218:219], v[62:63] op_sel_hi:[1,0]
	v_pk_mul_f32 v[22:23], v[22:23], v[56:57]
	v_and_b32_e32 v55, 0xffff0000, v65
	v_pk_mul_f32 v[22:23], v[52:53], v[22:23]
	v_lshlrev_b32_e32 v52, 16, v13
	v_and_b32_e32 v53, 0xffff0000, v13
	v_mul_f32_e32 v12, 0xbfb8aa3b, v52
	v_exp_f32_e32 v13, v12
	v_mul_f32_e32 v12, 0xbfb8aa3b, v53
	v_exp_f32_e32 v54, v12
	v_cvt_pk_bf16_f32 v12, v22, v23
	v_add_f32_e32 v13, 1.0, v13
	v_rcp_f32_e32 v22, v13
	v_add_f32_e32 v13, 1.0, v54
	v_rcp_f32_e32 v23, v13
	v_lshlrev_b32_e32 v54, 16, v65
	v_pk_mul_f32 v[20:21], v[20:21], v[54:55]
	v_pk_mul_f32 v[68:69], v[220:221], v[62:63] op_sel_hi:[1,0]
	v_pk_mul_f32 v[22:23], v[22:23], v[52:53]
	v_and_b32_e32 v53, 0xffff0000, v58
	v_pk_mul_f32 v[20:21], v[22:23], v[20:21]
	v_lshlrev_b32_e32 v22, 16, v14
	v_and_b32_e32 v23, 0xffff0000, v14
	v_mul_f32_e32 v13, 0xbfb8aa3b, v22
	v_exp_f32_e32 v14, v13
	v_mul_f32_e32 v13, 0xbfb8aa3b, v23
	v_exp_f32_e32 v52, v13
	v_cvt_pk_bf16_f32 v13, v20, v21
	v_add_f32_e32 v14, 1.0, v14
	v_rcp_f32_e32 v20, v14
	v_add_f32_e32 v14, 1.0, v52
	v_rcp_f32_e32 v21, v14
	v_lshlrev_b32_e32 v52, 16, v58
	v_pk_mul_f32 v[52:53], v[68:69], v[52:53]
	v_pk_mul_f32 v[66:67], v[222:223], v[62:63] op_sel_hi:[1,0]
	v_pk_mul_f32 v[20:21], v[20:21], v[22:23]
	v_lshlrev_b32_e32 v22, 16, v15
	v_and_b32_e32 v23, 0xffff0000, v15
	v_mul_f32_e32 v14, 0xbfb8aa3b, v22
	v_exp_f32_e32 v15, v14
	v_mul_f32_e32 v14, 0xbfb8aa3b, v23
	v_pk_mul_f32 v[20:21], v[20:21], v[52:53]
	v_exp_f32_e32 v52, v14
	v_add_f32_e32 v15, 1.0, v15
	v_cvt_pk_bf16_f32 v14, v20, v21
	v_rcp_f32_e32 v20, v15
	v_add_f32_e32 v15, 1.0, v52
	v_rcp_f32_e32 v21, v15
	v_lshlrev_b32_e32 v52, 16, v59
	v_and_b32_e32 v53, 0xffff0000, v59
	v_pk_mul_f32 v[52:53], v[66:67], v[52:53]
	v_pk_mul_f32 v[54:55], v[20:21], v[22:23]
	v_pk_mul_f32 v[56:57], v[54:55], v[52:53]
	v_cndmask_b32_e64 v50, v50, v46, s[6:7]
	v_lshlrev_b32_e32 v46, 16, v8
	v_cvt_pk_bf16_f32 v15, v56, v57
	v_cndmask_b32_e64 v51, v51, v47, s[6:7]
	v_and_b32_e32 v47, 0xffff0000, v8
	v_mul_f32_e32 v8, 0xbfb8aa3b, v46
	global_store_dwordx4 v[60:61], v[12:15], off offset:16
	v_exp_f32_e32 v8, v8
	v_cndmask_b32_e64 v41, v41, v37, s[6:7]
	s_waitcnt lgkmcnt(0)
; #define LBAR() do { asm volatile("s_waitcnt lgkmcnt(0)" ::: "memory"); __builtin_amdgcn_s_barrier(); asm volatile("" ::: "memory"); } while (0)
; #define GZLOAD(ZR, chunk) do { const bf16_t* zp_ = proj + (size_t)(b * SEQ + (chunk) * 64 + lane) * NINP + C_GZ + h * 64 + 32 * hc; \
;         _Pragma("unroll") for (int k = 0; k < 4; ++k) ZR[k] = *(const u32x4*)(zp_ + 8 * k); } while (0)
; DI void gdn_scan(const Ctx& c, int bh, const unsigned char* gbase, const float* GL, bf16_t* proj, const float* normw) {
;     ...
;         for (int n = 0; n < 64; n += 2) {
;             LBAR(); if (n > 0) GHELP(n - 1, zB); GZLOAD(zB, n + 1);
;             LBAR(); GHELP(n, zA); { const int nx = n + 2 < 64 ? n + 2 : 63; GZLOAD(zA, nx); }
	v_pk_mul_f32 v[12:13], v[226:227], v[62:63] op_sel_hi:[1,0]
	v_pk_mul_f32 v[22:23], v[228:229], v[62:63] op_sel_hi:[1,0]
	v_cndmask_b32_e64 v52, v49, v45, s[6:7]
	v_mul_f32_e32 v45, 0xbfb8aa3b, v47
	v_exp_f32_e32 v45, v45
	v_add_f32_e32 v8, 1.0, v8
	v_cndmask_b32_e64 v49, v48, v44, s[6:7]
	v_rcp_f32_e32 v44, v8
	v_add_f32_e32 v8, 1.0, v45
	v_rcp_f32_e32 v45, v8
	v_pk_mul_f32 v[14:15], v[224:225], v[62:63] op_sel_hi:[1,0]
	v_lshlrev_b32_e32 v48, 16, v49
	v_and_b32_e32 v49, 0xffff0000, v49
	v_pk_mul_f32 v[14:15], v[14:15], v[48:49]
	v_pk_mul_f32 v[44:45], v[44:45], v[46:47]
	v_and_b32_e32 v47, 0xffff0000, v52
	v_pk_mul_f32 v[14:15], v[44:45], v[14:15]
	v_lshlrev_b32_e32 v44, 16, v9
	v_and_b32_e32 v45, 0xffff0000, v9
	v_mul_f32_e32 v8, 0xbfb8aa3b, v44
	v_exp_f32_e32 v9, v8
	v_mul_f32_e32 v8, 0xbfb8aa3b, v45
	v_exp_f32_e32 v46, v8
	v_cvt_pk_bf16_f32 v8, v14, v15
	v_add_f32_e32 v9, 1.0, v9
	v_rcp_f32_e32 v14, v9
	v_add_f32_e32 v9, 1.0, v46
	v_rcp_f32_e32 v15, v9
	v_lshlrev_b32_e32 v46, 16, v52
	v_pk_mul_f32 v[12:13], v[12:13], v[46:47]
	v_pk_mul_f32 v[20:21], v[230:231], v[62:63] op_sel_hi:[1,0]
	v_pk_mul_f32 v[14:15], v[14:15], v[44:45]
	v_and_b32_e32 v45, 0xffff0000, v50
	v_pk_mul_f32 v[12:13], v[14:15], v[12:13]
	v_lshlrev_b32_e32 v14, 16, v10
	v_and_b32_e32 v15, 0xffff0000, v10
	v_mul_f32_e32 v9, 0xbfb8aa3b, v14
	v_exp_f32_e32 v10, v9
	v_mul_f32_e32 v9, 0xbfb8aa3b, v15
	v_exp_f32_e32 v44, v9
	v_cvt_pk_bf16_f32 v9, v12, v13
	v_add_f32_e32 v10, 1.0, v10
	v_rcp_f32_e32 v12, v10
	v_add_f32_e32 v10, 1.0, v44
	v_rcp_f32_e32 v13, v10
	v_lshlrev_b32_e32 v44, 16, v50
	v_pk_mul_f32 v[22:23], v[22:23], v[44:45]
	v_cndmask_b32_e64 v37, v40, v36, s[6:7]
	v_pk_mul_f32 v[12:13], v[12:13], v[14:15]
	v_lshlrev_b32_e32 v14, 16, v11
	v_and_b32_e32 v15, 0xffff0000, v11
	v_mul_f32_e32 v10, 0xbfb8aa3b, v14
	v_exp_f32_e32 v11, v10
	v_mul_f32_e32 v10, 0xbfb8aa3b, v15
	v_pk_mul_f32 v[12:13], v[12:13], v[22:23]
	v_exp_f32_e32 v22, v10
	v_add_f32_e32 v11, 1.0, v11
	v_cvt_pk_bf16_f32 v10, v12, v13
	v_rcp_f32_e32 v12, v11
	v_add_f32_e32 v11, 1.0, v22
	v_rcp_f32_e32 v13, v11
	v_lshlrev_b32_e32 v22, 16, v51
	v_and_b32_e32 v23, 0xffff0000, v51
	v_pk_mul_f32 v[20:21], v[20:21], v[22:23]
	v_pk_mul_f32 v[22:23], v[12:13], v[14:15]
	v_pk_mul_f32 v[44:45], v[22:23], v[20:21]
	v_cvt_pk_bf16_f32 v11, v44, v45
	global_store_dwordx4 v[60:61], v[8:11], off offset:32
	v_lshlrev_b32_e32 v36, 16, v37
	v_and_b32_e32 v37, 0xffff0000, v37
	s_waitcnt lgkmcnt(0)
	v_pk_mul_f32 v[8:9], v[234:235], v[62:63] op_sel_hi:[1,0]
	v_pk_mul_f32 v[14:15], v[236:237], v[62:63] op_sel_hi:[1,0]
	v_lshlrev_b32_e32 v20, 16, v4
	v_and_b32_e32 v21, 0xffff0000, v4
	v_mul_f32_e32 v4, 0xbfb8aa3b, v20
	v_pk_mul_f32 v[10:11], v[232:233], v[62:63] op_sel_hi:[1,0]
	v_pk_mul_f32 v[12:13], v[238:239], v[62:63] op_sel_hi:[1,0]
	v_exp_f32_e32 v4, v4
	v_mul_f32_e32 v22, 0xbfb8aa3b, v21
	v_exp_f32_e32 v23, v22
	v_pk_mul_f32 v[10:11], v[10:11], v[36:37]
	v_add_f32_e32 v4, 1.0, v4
	v_rcp_f32_e32 v22, v4
	v_add_f32_e32 v4, 1.0, v23
	v_rcp_f32_e32 v23, v4
	v_cndmask_b32_e64 v38, v42, v38, s[6:7]
	v_cndmask_b32_e64 v39, v43, v39, s[6:7]
	s_mov_b32 s33, s65
	v_pk_mul_f32 v[20:21], v[22:23], v[20:21]
	v_and_b32_e32 v23, 0xffff0000, v41
	v_pk_mul_f32 v[10:11], v[20:21], v[10:11]
	v_lshlrev_b32_e32 v20, 16, v5
	v_and_b32_e32 v21, 0xffff0000, v5
	v_mul_f32_e32 v4, 0xbfb8aa3b, v20
	v_exp_f32_e32 v5, v4
	v_mul_f32_e32 v4, 0xbfb8aa3b, v21
	v_exp_f32_e32 v22, v4
	v_cvt_pk_bf16_f32 v4, v10, v11
	v_add_f32_e32 v5, 1.0, v5
	v_rcp_f32_e32 v10, v5
	v_add_f32_e32 v5, 1.0, v22
	v_rcp_f32_e32 v11, v5
	v_lshlrev_b32_e32 v22, 16, v41
	v_pk_mul_f32 v[8:9], v[8:9], v[22:23]
	v_pk_mul_f32 v[10:11], v[10:11], v[20:21]
	s_nop 0
	v_pk_mul_f32 v[8:9], v[10:11], v[8:9]
	v_lshlrev_b32_e32 v10, 16, v6
	v_and_b32_e32 v11, 0xffff0000, v6
	v_mul_f32_e32 v5, 0xbfb8aa3b, v10
	v_exp_f32_e32 v6, v5
	v_mul_f32_e32 v5, 0xbfb8aa3b, v11
	v_exp_f32_e32 v20, v5
	v_cvt_pk_bf16_f32 v5, v8, v9
	v_add_f32_e32 v6, 1.0, v6
	v_rcp_f32_e32 v8, v6
	v_add_f32_e32 v6, 1.0, v20
	v_rcp_f32_e32 v9, v6
	v_lshlrev_b32_e32 v20, 16, v38
	v_and_b32_e32 v21, 0xffff0000, v38
	v_pk_mul_f32 v[14:15], v[14:15], v[20:21]
	v_pk_mul_f32 v[8:9], v[8:9], v[10:11]
	v_lshlrev_b32_e32 v10, 16, v7
	v_and_b32_e32 v11, 0xffff0000, v7
	v_mul_f32_e32 v6, 0xbfb8aa3b, v10
	v_exp_f32_e32 v7, v6
	v_mul_f32_e32 v6, 0xbfb8aa3b, v11
	v_pk_mul_f32 v[8:9], v[8:9], v[14:15]
	v_exp_f32_e32 v14, v6
	v_add_f32_e32 v7, 1.0, v7
	v_cvt_pk_bf16_f32 v6, v8, v9
	v_rcp_f32_e32 v8, v7
	v_add_f32_e32 v7, 1.0, v14
	v_rcp_f32_e32 v9, v7
	v_lshlrev_b32_e32 v14, 16, v39
	v_and_b32_e32 v15, 0xffff0000, v39
	v_pk_mul_f32 v[12:13], v[12:13], v[14:15]
	v_pk_mul_f32 v[8:9], v[8:9], v[10:11]
	s_nop 0
	v_pk_mul_f32 v[8:9], v[8:9], v[12:13]
	s_nop 0
	v_cvt_pk_bf16_f32 v7, v8, v9
	global_store_dwordx4 v[60:61], v[4:7], off offset:48
	s_branch .LBB0_2195
.Lnwl_init_1:
	v_mov_b32_e32 v240, s75
	ds_read_b128 v[208:211], v240
	ds_read_b128 v[212:215], v240 offset:16
	ds_read_b128 v[216:219], v240 offset:32
	ds_read_b128 v[220:223], v240 offset:48
	ds_read_b128 v[224:227], v240 offset:64
	ds_read_b128 v[228:231], v240 offset:80
	ds_read_b128 v[232:235], v240 offset:96
	ds_read_b128 v[236:239], v240 offset:112
	s_branch .LBB0_2195

; DI float fexp2(float x) { return __builtin_amdgcn_exp2f(x); }
; DI float half_max(float v) { const unsigned u = __float_as_uint(v); auto rr = __builtin_amdgcn_permlane32_swap(u, u, false, false); return fmaxf(__uint_as_float(rr[0]), __uint_as_float(rr[1])); }
; template <int MODE>
; DI void attn_unit(const Ctx& c, int bh, int qb, const bf16_t* Qp, int qpitch, const bf16_t* Kp, int kpitch, const bf16_t* VTp, bf16_t* Op, int opitch) {
;     ...
;                 float mx = fmaxf(s0[0], s1[0]);
; #pragma unroll
;                 for (int r = 1; r < 16; ++r) mx = fmaxf(mx, fmaxf(s0[r], s1[r]));
;                 mx = half_max(mx);
;                 if (__any(mx > mrun)) {
;                     const float mn_ = fmaxf(mrun, mx), al = fexp2(mrun - mn_); mrun = mn_; lrun *= al;
; #pragma unroll
;                     for (int r = 0; r < 16; ++r) { o[0][r] *= al; o[1][r] *= al; } }
.LBB0_2237:
	s_nop 8
	v_max_f32_e32 v2, v53, v37
	v_max_f32_e32 v230, v54, v38
	v_max3_f32 v2, v52, v36, v2
	v_max_f32_e32 v231, v55, v39
	v_max3_f32 v2, v2, v230, v231
	v_max_f32_e32 v230, v56, v40
	v_max_f32_e32 v231, v57, v41
	v_max3_f32 v2, v2, v230, v231
	v_max_f32_e32 v230, v58, v42
	v_max_f32_e32 v231, v59, v43
	v_max3_f32 v2, v2, v230, v231
	v_max_f32_e32 v230, v60, v44
	v_max_f32_e32 v231, v61, v45
	v_max3_f32 v2, v2, v230, v231
	v_max_f32_e32 v230, v62, v46
	v_max_f32_e32 v231, v63, v47
	v_max3_f32 v2, v2, v230, v231
	v_max_f32_e32 v230, v64, v48
	v_max_f32_e32 v231, v65, v49
	v_max3_f32 v2, v2, v230, v231
	v_max_f32_e32 v230, v66, v50
	v_max_f32_e32 v231, v67, v51
	v_max3_f32 v2, v2, v230, v231
	v_mov_b32_e32 v230, v2
	s_nop 1
	v_permlane32_swap_b32_e32 v2, v230
	v_max_f32_e32 v2, v2, v230
	v_cmp_gt_f32_e32 vcc, v2, v187
	s_cbranch_vccz .LBB0_2232
	v_max_f32_e32 v230, v187, v2
	v_sub_f32_e32 v2, v187, v230
	v_exp_f32_e32 v2, v2
	v_mov_b32_e32 v187, v230
	v_pk_mul_f32 v[34:35], v[34:35], v[2:3] op_sel_hi:[1,0]
	v_pk_mul_f32 v[32:33], v[32:33], v[2:3] op_sel_hi:[1,0]
	v_pk_mul_f32 v[30:31], v[30:31], v[2:3] op_sel_hi:[1,0]
	v_pk_mul_f32 v[28:29], v[28:29], v[2:3] op_sel_hi:[1,0]
	v_pk_mul_f32 v[26:27], v[26:27], v[2:3] op_sel_hi:[1,0]
	v_pk_mul_f32 v[24:25], v[24:25], v[2:3] op_sel_hi:[1,0]
	v_pk_mul_f32 v[22:23], v[22:23], v[2:3] op_sel_hi:[1,0]
	v_pk_mul_f32 v[20:21], v[20:21], v[2:3] op_sel_hi:[1,0]
	v_pk_mul_f32 v[18:19], v[18:19], v[2:3] op_sel_hi:[1,0]
	v_pk_mul_f32 v[16:17], v[16:17], v[2:3] op_sel_hi:[1,0]
	v_pk_mul_f32 v[14:15], v[14:15], v[2:3] op_sel_hi:[1,0]
	v_pk_mul_f32 v[12:13], v[12:13], v[2:3] op_sel_hi:[1,0]
	v_pk_mul_f32 v[10:11], v[10:11], v[2:3] op_sel_hi:[1,0]
	v_pk_mul_f32 v[8:9], v[8:9], v[2:3] op_sel_hi:[1,0]
	v_pk_mul_f32 v[6:7], v[6:7], v[2:3] op_sel_hi:[1,0]
	v_pk_mul_f32 v[4:5], v[4:5], v[2:3] op_sel_hi:[1,0]
	v_mul_f32_e32 v185, v185, v2
	s_branch .LBB0_2232
